# gdn_pre units remapped batch-per-XCD; G1->pre and pre->scan seams XCD-local; placement check moved to G1 start
# speedup vs baseline: 1.0040x; 1.0040x over previous
.LBB0_135:
	s_ashr_i32 s1, s2, 31
	s_lshr_b32 s0, s1, 29
	s_add_i32 s0, s2, s0
	s_ashr_i32 s3, s0, 3
	s_and_b32 s0, s0, -8
	s_ashr_i32 s50, s94, 31
	s_sub_i32 s0, s2, s0
	s_cmp_lt_i32 s0, 0
	v_writelane_b32 v240, s3, 28
	s_cselect_b64 s[4:5], -1, 0
	v_writelane_b32 v240, s4, 29
	s_lshl_b32 s3, s0, 7
	s_waitcnt lgkmcnt(0)
	v_mov_b64_e32 v[0:1], 0x400
	v_writelane_b32 v240, s5, 30
	v_writelane_b32 v240, s3, 31
	v_writelane_b32 v240, s0, 32
	s_mulk_i32 s0, 0x81
	s_add_u32 s4, s94, s2
	v_writelane_b32 v240, s0, 33
	s_addc_u32 s5, s50, s1
	v_writelane_b32 v240, s1, 34
	v_cmp_lt_i64_e64 s[0:1], s[4:5], v[0:1]
	s_barrier
	s_add_u32 s6, s92, 0x513600
	s_addc_u32 s7, s93, 0
	v_mov_b32_e32 v4, 0
	global_load_dword v5, v4, s[6:7] offset:0 sc1
	global_load_dword v6, v4, s[6:7] offset:256 sc1
	global_load_dword v7, v4, s[6:7] offset:512 sc1
	global_load_dword v8, v4, s[6:7] offset:768 sc1
	global_load_dword v9, v4, s[6:7] offset:1024 sc1
	global_load_dword v10, v4, s[6:7] offset:1280 sc1
	global_load_dword v11, v4, s[6:7] offset:1536 sc1
	global_load_dword v12, v4, s[6:7] offset:1792 sc1
	s_waitcnt vmcnt(0)
	v_mov_b32_e32 v13, -1
	v_mov_b32_e32 v14, 0
	v_min_u32_e32 v13, v13, v5
	v_add_u32_e32 v15, -1, v5
	v_and_b32_e32 v15, v15, v5
	v_or_b32_e32 v14, v14, v15
	v_min_u32_e32 v13, v13, v6
	v_add_u32_e32 v15, -1, v6
	v_and_b32_e32 v15, v15, v6
	v_or_b32_e32 v14, v14, v15
	v_min_u32_e32 v13, v13, v7
	v_add_u32_e32 v15, -1, v7
	v_and_b32_e32 v15, v15, v7
	v_or_b32_e32 v14, v14, v15
	v_min_u32_e32 v13, v13, v8
	v_add_u32_e32 v15, -1, v8
	v_and_b32_e32 v15, v15, v8
	v_or_b32_e32 v14, v14, v15
	v_min_u32_e32 v13, v13, v9
	v_add_u32_e32 v15, -1, v9
	v_and_b32_e32 v15, v15, v9
	v_or_b32_e32 v14, v14, v15
	v_min_u32_e32 v13, v13, v10
	v_add_u32_e32 v15, -1, v10
	v_and_b32_e32 v15, v15, v10
	v_or_b32_e32 v14, v14, v15
	v_min_u32_e32 v13, v13, v11
	v_add_u32_e32 v15, -1, v11
	v_and_b32_e32 v15, v15, v11
	v_or_b32_e32 v14, v14, v15
	v_min_u32_e32 v13, v13, v12
	v_add_u32_e32 v15, -1, v12
	v_and_b32_e32 v15, v15, v12
	v_or_b32_e32 v14, v14, v15
	v_cmp_ne_u32_e32 vcc, 0, v13
	s_nop 1
	v_cndmask_b32_e64 v13, 0, 1, vcc
	v_cmp_eq_u32_e32 vcc, 0, v14
	s_nop 1
	v_cndmask_b32_e32 v13, 0, v13, vcc
	v_mov_b32_e32 v14, 0x23ff8
	ds_write_b32 v14, v13
	v_mov_b32_e32 v15, 0
	ds_write_b32 v14, v15 offset:4
	s_waitcnt lgkmcnt(0)
	s_nop 0
	v_writelane_b32 v240, s0, 35
	s_nop 1
	v_writelane_b32 v240, s1, 36
	s_ashr_i32 s0, s4, 31
	s_lshr_b32 s0, s0, 29
	s_add_i32 s0, s4, s0
	s_ashr_i32 s1, s0, 3
	s_and_b32 s0, s0, -8
	s_sub_i32 s3, s4, s0
	s_cmp_lt_i32 s3, 0
	v_writelane_b32 v240, s1, 37
	s_cselect_b64 s[0:1], -1, 0
	v_writelane_b32 v240, s0, 38
	s_nop 1
	v_writelane_b32 v240, s1, 39
	s_lshl_b32 s0, s3, 7
	v_writelane_b32 v240, s0, 40
	v_writelane_b32 v240, s3, 41
	s_mul_i32 s0, s3, 0x81
	v_writelane_b32 v240, s0, 42
	s_add_u32 s6, s4, s94
	v_writelane_b32 v240, s4, 43
	s_addc_u32 s7, s5, s50
	v_cmp_lt_i64_e64 s[0:1], s[6:7], v[0:1]
	v_writelane_b32 v240, s5, 44
	s_nop 0
	v_writelane_b32 v240, s0, 45
	s_nop 1
	v_writelane_b32 v240, s1, 46
	s_ashr_i32 s0, s6, 31
	s_lshr_b32 s0, s0, 29
	s_add_i32 s0, s6, s0
	s_ashr_i32 s1, s0, 3
	s_and_b32 s0, s0, -8
	s_sub_i32 s3, s6, s0
	s_cmp_lt_i32 s3, 0
	v_writelane_b32 v240, s1, 47
	s_cselect_b64 s[0:1], -1, 0
	v_writelane_b32 v240, s0, 48
	s_nop 1
	v_writelane_b32 v240, s1, 49
	s_lshl_b32 s0, s3, 7
	v_writelane_b32 v240, s0, 50
	v_writelane_b32 v240, s3, 51
	s_mul_i32 s0, s3, 0x81
	v_writelane_b32 v240, s0, 52
	s_add_u32 s4, s6, s94
	v_writelane_b32 v240, s6, 53
	s_addc_u32 s5, s7, s50
	v_cmp_lt_i64_e64 s[0:1], s[4:5], v[0:1]
	v_writelane_b32 v240, s7, 54
	v_mbcnt_lo_u32_b32 v0, -1, 0
	v_mbcnt_hi_u32_b32 v0, -1, v0
	s_nop 0
	v_writelane_b32 v240, s0, 55
	s_nop 1
	v_writelane_b32 v240, s1, 56
	s_ashr_i32 s0, s4, 31
	s_lshr_b32 s0, s0, 29
	s_add_i32 s0, s4, s0
	s_ashr_i32 s1, s0, 3
	v_writelane_b32 v240, s1, 57
	s_and_b32 s0, s0, -8
	v_writelane_b32 v240, s4, 58
	s_sub_i32 s3, s4, s0
	s_cmp_lt_i32 s3, 0
	v_writelane_b32 v240, s5, 59
	s_cselect_b64 s[0:1], -1, 0
	v_writelane_b32 v240, s0, 60
	s_nop 1
	v_writelane_b32 v240, s1, 61
	s_lshl_b32 s0, s3, 7
	v_writelane_b32 v240, s0, 62
	s_mul_i32 s0, s3, 0x81
	v_writelane_b32 v241, s0, 0
	v_readlane_b32 s0, v242, 8
	s_cmpk_lt_i32 s2, 0x400
	v_writelane_b32 v240, s3, 63
	v_add_u32_e32 v1, s0, v0
	s_movk_i32 s0, 0x100
	v_cmp_gt_i32_e32 vcc, s0, v1
	s_cselect_b64 s[0:1], -1, 0
	v_cndmask_b32_e64 v0, 0, 1, s[0:1]
	v_cmp_ne_u32_e64 s[52:53], 1, v0
	s_and_saveexec_b64 s[0:1], vcc
	s_cbranch_execz .LBB0_144
	s_add_i32 s3, 0, 0x20000
	s_and_b64 vcc, exec, s[52:53]
	v_lshl_add_u32 v0, v1, 2, s3
	s_cbranch_vccnz .LBB0_138
	v_readlane_b32 s4, v240, 29
	v_readlane_b32 s5, v240, 30
	s_and_b64 s[4:5], s[4:5], exec
	v_readlane_b32 s3, v240, 31
	v_readlane_b32 s4, v240, 33
	s_cselect_b32 s3, s4, s3
	v_readlane_b32 s4, v240, 28
	s_add_i32 s3, s3, s4
	s_ashr_i32 s4, s3, 31
	s_lshr_b32 s4, s4, 25
	s_add_i32 s4, s3, s4
	s_and_b32 s5, s4, 0xff80
	s_sub_i32 s3, s3, s5
	s_bfe_i32 s5, s3, 0x80000
	s_bfe_u32 s5, s5, 0x3000c
	s_add_i32 s5, s3, s5
	s_and_b32 s5, s5, 0xf8
	s_sub_i32 s3, s3, s5
	s_sext_i32_i8 s3, s3
	s_lshl_b32 s4, s4, 4
	s_and_b32 s4, s4, 0xfffff800
	s_lshl_b32 s3, s3, 8
	s_add_i32 s3, s3, s4
	v_add_u32_e32 v2, s3, v1
	v_ashrrev_i32_e32 v3, 31, v2
	v_lshlrev_b64 v[2:3], 6, v[2:3]
	v_lshl_add_u64 v[14:15], s[92:93], 0, v[2:3]
	global_load_dwordx4 v[2:5], v[14:15], off
	global_load_dwordx4 v[6:9], v[14:15], off offset:16
	global_load_dwordx4 v[10:13], v[14:15], off offset:32
	s_nop 0
	global_load_dwordx4 v[14:17], v[14:15], off offset:48
	v_mov_b32_e32 v20, 0x358637bd
	s_mov_b32 s3, 0x800000
	s_waitcnt vmcnt(3)
	v_mov_b32_e32 v18, v3
	v_mov_b32_e32 v19, v4
	v_mov_b32_e32 v3, v5
	s_waitcnt vmcnt(2)
	v_mov_b32_e32 v4, v7
	v_mov_b32_e32 v5, v8
	v_mov_b32_e32 v7, v9
	v_pk_add_f32 v[2:3], v[18:19], v[2:3]
	v_pk_add_f32 v[4:5], v[4:5], v[6:7]
	v_pk_add_f32 v[2:3], v[2:3], v[2:3] op_sel:[0,1] op_sel_hi:[1,0]
	v_pk_add_f32 v[4:5], v[4:5], v[4:5] op_sel:[0,1] op_sel_hi:[1,0]
	s_waitcnt vmcnt(1)
	v_add_f32_e32 v8, v10, v11
	v_add_f32_e32 v10, v12, v13
	s_waitcnt vmcnt(0)
	v_mov_b32_e32 v9, v16
	v_mov_b32_e32 v11, v17
	v_mov_b32_e32 v3, v14
	v_mov_b32_e32 v5, v15
	v_pk_add_f32 v[6:7], v[8:9], v[10:11]
	v_pk_add_f32 v[2:3], v[2:3], v[4:5]
	s_nop 0
	v_pk_add_f32 v[2:3], v[2:3], v[6:7]
	s_nop 0
	v_add_f32_e32 v2, v2, v3
	v_fmac_f32_e32 v20, 0x3a800000, v2
	v_mul_f32_e32 v2, 0x4b800000, v20
	v_cmp_gt_f32_e32 vcc, s3, v20
	s_nop 1
	v_cndmask_b32_e32 v2, v20, v2, vcc
	v_rsq_f32_e32 v2, v2
	s_nop 0
	v_mul_f32_e32 v3, 0x45800000, v2
	v_cndmask_b32_e32 v2, v2, v3, vcc
	ds_write_b32 v0, v2

.LBB0_164:
	s_waitcnt vmcnt(0)
	v_readfirstlane_b32 s0, v194
	s_cmp_gt_u32 s0, 63
	s_waitcnt vmcnt(0)
	s_barrier
	s_cbranch_scc1 .LBB0_218
	v_mbcnt_lo_u32_b32 v0, -1, 0
	v_mbcnt_hi_u32_b32 v0, -1, v0
	s_nop 0
	v_cmp_eq_u32_e32 vcc, 0, v0
	s_and_saveexec_b64 s[0:1], vcc
	s_cbranch_execz .LBB0_217
	v_mov_b32_e32 v0, 0x23ff0
	s_waitcnt vmcnt(0) lgkmcnt(0)
	ds_read_b128 v[0:3], v0
	s_waitcnt lgkmcnt(0)
	v_readfirstlane_b32 s3, v2
	s_nop 0
	s_cmp_eq_u32 s3, 0
	s_cbranch_scc1 .Lfb_slow_0
	v_add_u32_e32 v3, 1, v3
	v_mov_b32_e32 v4, 0x23ffc
	ds_write_b32 v4, v3
	v_mul_lo_u32 v5, v3, v0
	s_getreg_b32 s3, hwreg(HW_REG_XCC_ID, 0, 4)
	s_and_b32 s3, s3, 7
	s_lshl_b32 s3, s3, 8
	s_add_u32 s3, s3, 0x3680
	s_add_u32 s4, s92, 0x510000
	s_addc_u32 s5, s93, 0
	v_mov_b32_e32 v6, s3
	v_mov_b32_e32 v7, 1
	global_atomic_add v6, v7, s[4:5]
	s_mov_b32 s8, 0
.Lfb_spin_0:
	global_load_dword v8, v6, s[4:5] sc1
	s_waitcnt vmcnt(0)
	v_cmp_ge_u32_e32 vcc, v8, v5
	s_cbranch_vccnz .Lfb_done_0
	s_sleep 1
	s_add_u32 s8, s8, 1
	s_cmp_lt_u32 s8, 0x40000
	s_cbranch_scc1 .Lfb_spin_0

.Lfb_slow_0:
	s_add_i32 s3, 0, 0x23ff0
	v_mov_b32_e32 v0, s3
	s_waitcnt vmcnt(0) expcnt(0) lgkmcnt(0)
	ds_read_b32 v2, v0
	s_add_i32 s3, 0, 0x23ff4
	v_mov_b32_e32 v0, s3
	ds_read_b32 v0, v0
	s_waitcnt lgkmcnt(1)
	v_cmp_ne_u32_e32 vcc, 0, v2
	s_cbranch_vccnz .LBB0_181
	s_mov_b32 s3, 1
	v_mov_b32_e32 v16, 0
	s_branch .LBB0_169
.LBB0_168:
	s_and_b64 vcc, exec, s[6:7]
	s_cbranch_vccnz .LBB0_176

.LBB0_197:
	s_andn2_saveexec_b64 s[4:5], s[4:5]
	s_cbranch_execz .LBB0_217
	v_mov_b32_e32 v1, 0x23ff8
	ds_read_b32 v1, v1
	s_waitcnt lgkmcnt(0)
	v_readfirstlane_b32 s3, v1
	s_nop 0
	s_cmp_lg_u32 s3, 0
	s_cbranch_scc1 .Lxloc_0
	s_mov_b64 s[4:5], exec
	buffer_wbl2 sc1
	s_waitcnt lgkmcnt(0)
	s_waitcnt vmcnt(0)
	v_mbcnt_lo_u32_b32 v1, s4, 0
	v_mbcnt_hi_u32_b32 v1, s5, v1
	v_cmp_eq_u32_e32 vcc, 0, v1
	s_and_saveexec_b64 s[6:7], vcc
	s_cbranch_execz .LBB0_200
	s_bcnt1_i32_b64 s3, s[4:5]
	v_readlane_b32 s4, v240, 24
	v_mov_b32_e32 v2, 0
	v_mov_b32_e32 v3, s3
	v_readlane_b32 s5, v240, 25
	s_nop 4
	global_atomic_add v2, v2, v3, s[4:5] sc0

.Lxloc_0:
	s_mov_b64 s[4:5], exec
	v_mbcnt_lo_u32_b32 v0, s4, 0
	v_mbcnt_hi_u32_b32 v0, s5, v0
	v_cmp_eq_u32_e32 vcc, 0, v0
	s_waitcnt vmcnt(0)
	buffer_inv sc1
	s_and_saveexec_b64 s[6:7], vcc
	s_cbranch_execz .LBB0_216
	s_bcnt1_i32_b64 s3, s[4:5]
	v_readlane_b32 s4, v240, 22
	v_mov_b32_e32 v0, 0
	v_mov_b32_e32 v1, s3
	v_readlane_b32 s5, v240, 23
	s_nop 4
	global_atomic_add v0, v1, s[4:5]

.LBB0_218:
	s_add_u32 s6, s92, 0x400000
	s_addc_u32 s8, s93, 0
	v_writelane_b32 v241, s52, 5
	s_add_u32 s0, s92, 0x500000
	s_addc_u32 s1, s93, 0
	v_writelane_b32 v241, s53, 6
	v_writelane_b32 v241, s0, 7
	s_lshr_b32 s5, s33, 8
	s_bfe_u32 s4, s33, 0x20006
	v_writelane_b32 v241, s1, 8
	s_lshl_b32 s0, s5, 10
	s_add_i32 s18, s0, 0
	s_cmp_eq_u32 s4, 0
	s_cselect_b64 s[10:11], -1, 0
	s_cmp_lg_u32 s4, 0
	s_cselect_b64 s[56:57], -1, 0
	s_mov_b32 s15, 0
	s_and_b32 s0, s51, 31
	s_lshl_b32 s0, s0, 1
	s_add_i32 s0, s0, s5
	s_lshr_b32 s72, s51, 5
	s_lshl_b32 s72, s72, 8
	s_lshr_b32 s1, s0, 3
	s_lshl_b32 s1, s1, 5
	s_add_i32 s72, s72, s1
	s_and_b32 s0, s0, 7
	s_add_i32 s72, s72, s0
	v_writelane_b32 v241, s10, 9
	s_and_b64 vcc, exec, s[10:11]
	s_waitcnt lgkmcnt(0)
	s_barrier
	v_writelane_b32 v241, s11, 10
	s_cbranch_vccnz .LBB0_220
	s_lshl_b32 s0, s72, 6
	s_and_b32 s0, s0, 0x7c0
	s_bfe_u32 s14, s72, 0x30005
	v_writelane_b32 v241, s0, 11
	s_add_i32 s18, s18, 0x23000
	s_cbranch_execz .LBB0_221
	s_branch .LBB0_224

.LBB0_224:
	s_add_u32 s55, s92, 0x9000000
	s_addc_u32 s3, s93, 0
	s_add_u32 s0, s90, 0x2000000
	s_addc_u32 s1, s91, 0
	s_add_u32 s16, s92, 0xb000000
	s_addc_u32 s17, s93, 0
	s_add_u32 s20, s92, 0xd000000
	s_addc_u32 s21, s93, 0
	v_writelane_b32 v241, s51, 12
	s_add_u32 s10, s92, 0xf000000
	v_writelane_b32 v241, s50, 13
	s_addc_u32 s11, s93, 0
	v_writelane_b32 v241, s10, 14
	s_mul_i32 s5, s5, 0x11800
	s_add_i32 s19, s5, 0
	v_writelane_b32 v241, s11, 15
	s_lshl_b32 s7, s4, 6
	s_lshl_b32 s10, s4, 4
	s_cmp_eq_u32 s4, 1
	s_cselect_b64 s[30:31], -1, 0
	s_lshl_b32 s5, s4, 1
	s_cmp_gt_u32 s4, 1
	s_cselect_b64 s[78:79], -1, 0
	s_cmp_eq_u32 s4, 3
	s_cselect_b64 s[24:25], -1, 0
	s_lshl_b32 s26, s4, 5
	s_or_b32 s4, s5, 1
	s_lshl_b32 s9, s49, 2
	s_lshl_b32 s5, s4, 1
	s_and_b32 s11, s9, 4
	s_and_b32 s27, s5, 6
	s_lshl_b32 s4, s4, 4
	s_and_b32 s5, s72, 31
	s_lshl_b64 s[12:13], s[14:15], 2
	s_add_u32 s28, s6, s12
	v_writelane_b32 v241, s9, 16
	s_addc_u32 s29, s8, s13
	v_writelane_b32 v241, s28, 17
	s_add_u32 s8, s84, s12
	s_addc_u32 s9, s85, s13
	v_writelane_b32 v241, s29, 18
	v_writelane_b32 v241, s8, 19
	v_mbcnt_hi_u32_b32 v159, -1, v146
	v_and_b32_e32 v97, 64, v159
	v_writelane_b32 v241, s9, 20
	s_add_u32 s8, s82, s12
	s_addc_u32 s9, s83, s13
	s_lshl_b32 s6, s72, 3
	s_mov_b32 s77, 0
	v_writelane_b32 v241, s8, 21
	s_movk_i32 s15, 0x1000
	s_add_i32 s84, s6, 0x40
	s_movk_i32 s85, 0x80
	v_mov_b32_e32 v85, 0
	s_movk_i32 s82, 0x1800
	s_mov_b64 s[28:29], 0x1000
	v_xor_b32_e32 v95, 1, v159
	v_add_u32_e32 v160, 64, v97
	v_xor_b32_e32 v144, 2, v159
	v_xor_b32_e32 v145, 4, v159
	v_xor_b32_e32 v146, 8, v159
	s_movk_i32 s83, 0x4000
	s_movk_i32 s95, 0x7000
	s_mov_b32 s33, 0xa000
	s_movk_i32 s54, 0x110
	s_mov_b32 s12, 0x800000
	s_movk_i32 s13, 0x90
	s_xor_b64 s[30:31], s[30:31], -1
	v_mov_b32_e32 v147, 0x3ecc95a3
	v_mov_b32_e32 v148, s19
	v_mov_b32_e32 v149, 0x100
	v_mov_b32_e32 v150, 0x7f800000
	s_mov_b64 s[36:37], 0x4000
	s_mov_b64 s[38:39], 0x7000
	s_mov_b64 s[40:41], 0xa000
	s_mov_b32 s6, 0x358637bd
	s_waitcnt lgkmcnt(0)
	s_barrier
	v_writelane_b32 v241, s9, 22
	s_branch .LBB0_228

.LBB0_227:
	v_mul_u32_u24_e32 v0, 0x90, v151
	v_lshrrev_b32_e32 v33, 3, v151
	v_add3_u32 v48, s19, v0, v24
	v_or_b32_e32 v0, s26, v151
	v_mov_b32_e32 v49, s19
	v_mad_u32_u24 v0, v0, s13, v49
	v_bitop3_b32 v1, v33, v32, s11 bitop3:0x36
	v_lshl_add_u32 v60, v1, 4, v0
	s_waitcnt lgkmcnt(0)
	s_barrier
	ds_read_b128 v[34:37], v60 offset:34816
	v_add_u32_e32 v50, 4, v32
	v_bitop3_b32 v1, v33, v50, s11 bitop3:0x36
	v_lshl_add_u32 v61, v1, 4, v0
	ds_read_b128 v[38:41], v61 offset:34816
	ds_read_b128 v[28:31], v48
	ds_read_b128 v[24:27], v48 offset:64
	s_waitcnt lgkmcnt(1)
	v_mfma_f32_16x16x32_bf16 v[0:3], v[34:37], v[28:31], 0
	s_add_u32 s8, s55, s48
	s_addc_u32 s9, s3, s49
	v_lshlrev_b64 v[58:59], 1, v[20:21]
	s_waitcnt lgkmcnt(0)
	v_mfma_f32_16x16x32_bf16 v[0:3], v[38:41], v[24:27], v[0:3]
	v_lshl_add_u64 v[54:55], s[8:9], 0, v[58:59]
	s_lshl_b32 s76, s26, 1
	v_lshl_add_u64 v[46:47], v[54:55], 0, s[76:77]
	v_lshlrev_b32_e32 v84, 8, v151
	v_or_b32_e32 v44, 0x1000, v84
	s_nop 2
	v_cvt_pk_bf16_f32 v0, v0, v1
	v_cvt_pk_bf16_f32 v1, v2, v3
	v_lshl_add_u64 v[2:3], v[46:47], 0, v[84:85]
	global_store_dwordx2 v[2:3], v[0:1], off
	ds_read_b128 v[20:23], v48 offset:2304
	ds_read_b128 v[16:19], v48 offset:2368
	s_waitcnt lgkmcnt(1)
	v_mfma_f32_16x16x32_bf16 v[0:3], v[34:37], v[20:23], 0
	v_mov_b32_e32 v45, v85
	v_or_b32_e32 v42, 0x2000, v84
	v_mov_b32_e32 v43, v85
	s_waitcnt lgkmcnt(0)
	v_mfma_f32_16x16x32_bf16 v[0:3], v[38:41], v[16:19], v[0:3]
	v_bitop3_b32 v32, v33, v32, s27 bitop3:0x36
	v_bitop3_b32 v33, v33, v50, s27 bitop3:0x36
	s_lshl_b32 s42, s4, 1
	s_mov_b32 s43, s77
	s_add_u32 s8, s0, s48
	s_nop 2
	v_cvt_pk_bf16_f32 v0, v0, v1
	v_cvt_pk_bf16_f32 v1, v2, v3
	v_lshl_add_u64 v[2:3], v[46:47], 0, v[44:45]
	global_store_dwordx2 v[2:3], v[0:1], off
	ds_read_b128 v[12:15], v48 offset:4608
	ds_read_b128 v[8:11], v48 offset:4672
	s_waitcnt lgkmcnt(1)
	v_mfma_f32_16x16x32_bf16 v[0:3], v[34:37], v[12:15], 0
	s_addc_u32 s9, s1, s49
	s_addk_i32 s72, 8
	s_addk_i32 s84, 0x40
	s_waitcnt lgkmcnt(0)
	v_mfma_f32_16x16x32_bf16 v[0:3], v[38:41], v[8:11], v[0:3]
	s_addk_i32 s85, 0x80
	s_cmpk_lg_i32 s85, 0x280
	s_nop 5
	v_cvt_pk_bf16_f32 v0, v0, v1
	v_cvt_pk_bf16_f32 v1, v2, v3
	v_lshl_add_u64 v[2:3], v[46:47], 0, v[42:43]
	global_store_dwordx2 v[2:3], v[0:1], off
	ds_read_b128 v[4:7], v48 offset:6912
	ds_read_b128 v[0:3], v48 offset:6976
	s_waitcnt lgkmcnt(1)
	v_mfma_f32_16x16x32_bf16 v[34:37], v[34:37], v[4:7], 0
	s_waitcnt lgkmcnt(0)
	v_mfma_f32_16x16x32_bf16 v[34:37], v[38:41], v[0:3], v[34:37]
	v_or_b32_e32 v40, 0x3000, v84
	v_mov_b32_e32 v41, v85
	s_nop 5
	v_cvt_pk_bf16_f32 v34, v34, v35
	v_cvt_pk_bf16_f32 v35, v36, v37
	v_lshl_add_u64 v[36:37], v[46:47], 0, v[40:41]
	global_store_dwordx2 v[36:37], v[34:35], off
	v_or_b32_e32 v34, s4, v151
	v_mad_u32_u24 v34, v34, s13, v49
	v_lshl_add_u32 v32, v32, 4, v34
	ds_read_b128 v[46:49], v32 offset:34816
	v_lshl_add_u32 v36, v33, 4, v34
	ds_read_b128 v[50:53], v36 offset:34816
	v_lshl_add_u64 v[34:35], v[54:55], 0, s[42:43]
	s_waitcnt lgkmcnt(1)
	v_mfma_f32_16x16x32_bf16 v[54:57], v[46:49], v[28:31], 0
	s_waitcnt lgkmcnt(0)
	v_mfma_f32_16x16x32_bf16 v[54:57], v[50:53], v[24:27], v[54:57]
	s_nop 7
	v_cvt_pk_bf16_f32 v38, v54, v55
	v_cvt_pk_bf16_f32 v39, v56, v57
	v_lshl_add_u64 v[54:55], v[34:35], 0, v[84:85]
	global_store_dwordx2 v[54:55], v[38:39], off
	v_mfma_f32_16x16x32_bf16 v[54:57], v[46:49], v[20:23], 0
	v_mfma_f32_16x16x32_bf16 v[54:57], v[50:53], v[16:19], v[54:57]
	s_nop 7
	v_cvt_pk_bf16_f32 v38, v54, v55
	v_cvt_pk_bf16_f32 v39, v56, v57
	v_lshl_add_u64 v[54:55], v[34:35], 0, v[44:45]
	global_store_dwordx2 v[54:55], v[38:39], off
	v_mfma_f32_16x16x32_bf16 v[54:57], v[46:49], v[12:15], 0
	v_mfma_f32_16x16x32_bf16 v[46:49], v[46:49], v[4:7], 0
	v_mfma_f32_16x16x32_bf16 v[54:57], v[50:53], v[8:11], v[54:57]
	v_mfma_f32_16x16x32_bf16 v[46:49], v[50:53], v[0:3], v[46:49]
	s_nop 6
	v_cvt_pk_bf16_f32 v38, v54, v55
	v_cvt_pk_bf16_f32 v39, v56, v57
	v_lshl_add_u64 v[54:55], v[34:35], 0, v[42:43]
	global_store_dwordx2 v[54:55], v[38:39], off
	v_cvt_pk_bf16_f32 v38, v46, v47
	v_cvt_pk_bf16_f32 v39, v48, v49
	v_lshl_add_u64 v[34:35], v[34:35], 0, v[40:41]
	global_store_dwordx2 v[34:35], v[38:39], off
	ds_read_b128 v[48:51], v60 offset:53248
	ds_read_b128 v[52:55], v61 offset:53248
	v_lshl_add_u64 v[46:47], s[8:9], 0, v[58:59]
	s_waitcnt lgkmcnt(1)
	v_mfma_f32_16x16x32_bf16 v[56:59], v[48:51], v[28:31], 0
	v_lshl_add_u64 v[34:35], v[46:47], 0, s[76:77]
	v_lshl_add_u64 v[46:47], v[46:47], 0, s[42:43]
	s_waitcnt lgkmcnt(0)
	v_mfma_f32_16x16x32_bf16 v[56:59], v[52:55], v[24:27], v[56:59]
	s_nop 7
	v_cvt_pk_bf16_f32 v38, v56, v57
	v_cvt_pk_bf16_f32 v39, v58, v59
	v_lshl_add_u64 v[56:57], v[34:35], 0, v[84:85]
	global_store_dwordx2 v[56:57], v[38:39], off
	v_mfma_f32_16x16x32_bf16 v[56:59], v[48:51], v[20:23], 0
	v_mfma_f32_16x16x32_bf16 v[56:59], v[52:55], v[16:19], v[56:59]
	s_nop 7
	v_cvt_pk_bf16_f32 v38, v56, v57
	v_cvt_pk_bf16_f32 v39, v58, v59
	v_lshl_add_u64 v[56:57], v[34:35], 0, v[44:45]
	global_store_dwordx2 v[56:57], v[38:39], off
	v_mfma_f32_16x16x32_bf16 v[56:59], v[48:51], v[12:15], 0
	v_mfma_f32_16x16x32_bf16 v[48:51], v[48:51], v[4:7], 0
	v_mfma_f32_16x16x32_bf16 v[56:59], v[52:55], v[8:11], v[56:59]
	v_mfma_f32_16x16x32_bf16 v[48:51], v[52:55], v[0:3], v[48:51]
	s_nop 6
	v_cvt_pk_bf16_f32 v38, v56, v57
	v_cvt_pk_bf16_f32 v39, v58, v59
	v_lshl_add_u64 v[56:57], v[34:35], 0, v[42:43]
	global_store_dwordx2 v[56:57], v[38:39], off
	v_cvt_pk_bf16_f32 v38, v48, v49
	v_cvt_pk_bf16_f32 v39, v50, v51
	v_lshl_add_u64 v[34:35], v[34:35], 0, v[40:41]
	global_store_dwordx2 v[34:35], v[38:39], off
	ds_read_b128 v[32:35], v32 offset:53248
	ds_read_b128 v[36:39], v36 offset:53248
	s_waitcnt lgkmcnt(1)
	v_mfma_f32_16x16x32_bf16 v[28:31], v[32:35], v[28:31], 0
	v_mfma_f32_16x16x32_bf16 v[20:23], v[32:35], v[20:23], 0
	v_mfma_f32_16x16x32_bf16 v[12:15], v[32:35], v[12:15], 0
	v_mfma_f32_16x16x32_bf16 v[4:7], v[32:35], v[4:7], 0
	s_waitcnt lgkmcnt(0)
	v_mfma_f32_16x16x32_bf16 v[24:27], v[36:39], v[24:27], v[28:31]
	v_mfma_f32_16x16x32_bf16 v[16:19], v[36:39], v[16:19], v[20:23]
	v_mfma_f32_16x16x32_bf16 v[8:11], v[36:39], v[8:11], v[12:15]
	s_nop 5
	v_cvt_pk_bf16_f32 v24, v24, v25
	v_cvt_pk_bf16_f32 v25, v26, v27
	v_lshl_add_u64 v[26:27], v[46:47], 0, v[84:85]
	v_mfma_f32_16x16x32_bf16 v[0:3], v[36:39], v[0:3], v[4:7]
	v_cvt_pk_bf16_f32 v16, v16, v17
	v_cvt_pk_bf16_f32 v17, v18, v19
	v_lshl_add_u64 v[18:19], v[46:47], 0, v[44:45]
	v_cvt_pk_bf16_f32 v8, v8, v9
	v_cvt_pk_bf16_f32 v9, v10, v11
	v_lshl_add_u64 v[10:11], v[46:47], 0, v[42:43]
	s_nop 1
	v_cvt_pk_bf16_f32 v0, v0, v1
	v_cvt_pk_bf16_f32 v1, v2, v3
	v_lshl_add_u64 v[2:3], v[46:47], 0, v[40:41]
	global_store_dwordx2 v[26:27], v[24:25], off
	global_store_dwordx2 v[18:19], v[16:17], off
	global_store_dwordx2 v[10:11], v[8:9], off
	global_store_dwordx2 v[2:3], v[0:1], off
	s_barrier
	s_cbranch_scc0 .LBB0_308
.LBB0_228:
	s_ashr_i32 s8, s72, 8
	s_mov_b32 s9, s14
	s_and_b32 s42, s72, 31
	v_mbcnt_lo_u32_b32 v152, -1, 0
	v_mbcnt_hi_u32_b32 v152, -1, v152
	s_lshl_b32 s44, s8, 11
	s_add_i32 s8, s85, 0xffffff80
	s_and_b32 s8, s8, 0x80
	v_or_b32_e32 v28, s7, v152
	s_lshl_b32 s8, s8, 2
	s_add_i32 s76, s18, s8
	v_ashrrev_i32_e32 v75, 2, v28
	s_lshl_b32 s8, s9, 7
	v_and_b32_e32 v72, -4, v75
	s_ashr_i32 s9, s8, 31
	v_lshl_add_u32 v73, s42, 6, v72
	s_add_i32 s45, s44, -3
	s_lshl_b64 s[42:43], s[8:9], 1
	v_and_b32_e32 v151, 15, v152
	s_add_u32 s42, s96, s42
	s_addc_u32 s43, s97, s43
	v_lshlrev_b32_e32 v84, 4, v151
	v_max_i32_e32 v0, 3, v73
	v_lshl_add_u64 v[58:59], s[42:43], 0, v[84:85]
	v_add_u32_e32 v60, s45, v0
	v_mad_i64_i32 v[34:35], s[42:43], v60, s82, v[58:59]
	global_load_dwordx4 v[8:11], v[34:35], off nt
	v_or_b32_e32 v74, 1, v73
	v_max_i32_e32 v0, 3, v74
	v_add_u32_e32 v62, s45, v0
	v_mad_i64_i32 v[38:39], s[42:43], v62, s82, v[58:59]
	global_load_dwordx4 v[4:7], v[38:39], off nt
	v_or_b32_e32 v76, 2, v73
	v_max_i32_e32 v0, 3, v76
	v_add_u32_e32 v66, s45, v0
	v_or_b32_e32 v0, 3, v73
	v_max_i32_e32 v0, 3, v0
	v_add_u32_e32 v77, s45, v0
	v_lshl_add_u32 v87, v72, 2, s76
	v_mov_b32_e32 v0, s76
	ds_read_b128 v[30:33], v87
	ds_read_b32 v29, v0 offset:252
	v_mad_i64_i32 v[42:43], s[42:43], v66, s82, v[58:59]
	v_mad_i64_i32 v[46:47], s[42:43], v77, s82, v[58:59]
	s_waitcnt lgkmcnt(1)
	v_mul_f32_e32 v0, 0x3fb8aa3b, v30
	s_waitcnt lgkmcnt(0)
	v_sub_f32_e32 v30, v29, v30
	v_mul_f32_e32 v30, 0x3fb8aa3b, v30
	v_exp_f32_e32 v88, v30
	v_mul_f32_e32 v30, 0x3fb8aa3b, v31
	v_exp_f32_e32 v94, v30
	v_sub_f32_e32 v30, v29, v31
	v_mul_f32_e32 v30, 0x3fb8aa3b, v30
	v_exp_f32_e32 v89, v30
	v_mul_f32_e32 v30, 0x3fb8aa3b, v32
	v_exp_f32_e32 v90, v30
	v_sub_f32_e32 v30, v29, v32
	v_sub_f32_e32 v29, v29, v33
	global_load_dwordx4 v[20:23], v[42:43], off nt
	global_load_dwordx4 v[12:15], v[46:47], off nt
	v_mul_f32_e32 v29, 0x3fb8aa3b, v29
	v_cmp_gt_i32_e32 vcc, 3, v73
	v_lshl_add_u64 v[70:71], v[58:59], 0, s[28:29]
	v_exp_f32_e32 v86, v0
	v_max_i32_e32 v0, -1, v73
	v_exp_f32_e32 v93, v29
	v_add3_u32 v78, v0, s44, 1
	v_max_i32_e32 v16, -2, v73
	v_max_i32_e32 v24, -3, v73
	global_load_dwordx4 v[38:41], v[38:39], off offset:2048 nt
	v_mad_i64_i32 v[50:51], s[42:43], v78, s82, v[58:59]
	v_add3_u32 v79, v16, s44, 2
	v_add3_u32 v80, v24, s44, 3
	global_load_dwordx4 v[0:3], v[50:51], off nt
	v_mad_i64_i32 v[54:55], s[42:43], v79, s82, v[58:59]
	v_mad_i64_i32 v[56:57], s[42:43], v80, s82, v[58:59]
	v_mul_f32_e32 v30, 0x3fb8aa3b, v30
	v_mad_i64_i32 v[58:59], s[42:43], v60, s82, v[70:71]
	v_cmp_gt_i32_e64 s[52:53], 3, v74
	global_load_dwordx4 v[24:27], v[56:57], off nt
	v_exp_f32_e32 v92, v30
	global_load_dwordx4 v[34:37], v[34:35], off offset:2048 nt
	v_mul_f32_e32 v30, 0x3fb8aa3b, v33
	global_load_dwordx4 v[58:61], v[58:59], off nt
	v_exp_f32_e32 v96, v30
	global_load_dwordx4 v[16:19], v[54:55], off nt
	global_load_dwordx4 v[30:33], v[54:55], off offset:2048 nt
	v_cmp_gt_i32_e64 s[44:45], 3, v76
	global_load_dwordx4 v[50:53], v[50:51], off offset:2048 nt
	v_cmp_gt_i32_e64 s[50:51], -3, v73
	global_load_dwordx4 v[54:57], v[56:57], off offset:2048 nt
	v_cmp_gt_i32_e64 s[48:49], -2, v73
	global_load_dwordx4 v[42:45], v[42:43], off offset:2048 nt
	v_lshlrev_b32_e32 v179, 3, v151
	global_load_dwordx4 v[46:49], v[46:47], off offset:2048 nt
	v_add_u32_e32 v74, s19, v84
	s_waitcnt vmcnt(14)
	v_cndmask_b32_e64 v29, v8, 0, vcc
	v_cndmask_b32_e64 v100, v9, 0, vcc
	v_mad_i64_i32 v[8:9], s[42:43], v62, s82, v[70:71]
	global_load_dwordx4 v[62:65], v[8:9], off nt
	v_cndmask_b32_e64 v101, v10, 0, vcc
	s_waitcnt vmcnt(14)
	v_cndmask_b32_e64 v108, v4, 0, s[52:53]
	v_cndmask_b32_e64 v106, v5, 0, s[52:53]
	v_mad_i64_i32 v[4:5], s[46:47], v78, s82, v[70:71]
	v_cndmask_b32_e64 v104, v6, 0, s[52:53]
	v_cndmask_b32_e64 v103, v7, 0, s[52:53]
	global_load_dwordx4 v[4:7], v[4:5], off nt
	v_mad_i64_i32 v[8:9], s[42:43], v66, s82, v[70:71]
	global_load_dwordx4 v[66:69], v[8:9], off nt
	v_mad_i64_i32 v[8:9], s[42:43], v77, s82, v[70:71]
	v_cmp_gt_i32_e64 s[42:43], 0, v73
	v_cndmask_b32_e64 v102, v11, 0, vcc
	global_load_dwordx4 v[8:11], v[8:9], off nt
	s_waitcnt vmcnt(16)
	v_cndmask_b32_e64 v105, v22, 0, s[44:45]
	s_waitcnt vmcnt(15)
	v_cndmask_b32_e64 v110, v12, 0, s[42:43]
	v_cndmask_b32_e64 v111, v13, 0, s[42:43]
	v_mad_i64_i32 v[12:13], s[46:47], v79, s82, v[70:71]
	global_load_dwordx4 v[76:79], v[12:13], off nt
	v_mad_i64_i32 v[12:13], s[46:47], v80, s82, v[70:71]
	global_load_dwordx4 v[80:83], v[12:13], off nt
	v_cmp_gt_i32_e64 s[46:47], -1, v73
	v_cndmask_b32_e64 v22, v23, 0, s[44:45]
	s_waitcnt vmcnt(16)
	v_cndmask_b32_e64 v128, v38, 0, s[52:53]
	v_cndmask_b32_e64 v126, v39, 0, s[52:53]
	v_cndmask_b32_e64 v140, v40, 0, s[52:53]
	v_cndmask_b32_e64 v193, v41, 0, s[52:53]
	v_cndmask_b32_e64 v107, v14, 0, s[42:43]
	v_cndmask_b32_e64 v23, v15, 0, s[42:43]
	s_waitcnt vmcnt(15)
	v_cndmask_b32_e64 v14, v0, 0, s[46:47]
	v_cndmask_b32_e64 v15, v1, 0, s[46:47]
	v_lshlrev_b32_e32 v0, 5, v151
	v_mov_b32_e32 v1, v85
	v_cndmask_b32_e64 v109, v20, 0, s[44:45]
	v_cndmask_b32_e64 v20, v2, 0, s[46:47]
	v_cndmask_b32_e64 v112, v3, 0, s[46:47]
	v_cndmask_b32_e64 v21, v21, 0, s[44:45]
	s_waitcnt vmcnt(14)
	v_cndmask_b32_e64 v199, v24, 0, s[50:51]
	v_cndmask_b32_e64 v200, v25, 0, s[50:51]
	s_waitcnt vmcnt(13)
	v_cndmask_b32_e64 v135, v34, 0, vcc
	v_cndmask_b32_e64 v137, v35, 0, vcc
	v_cndmask_b32_e64 v141, v36, 0, vcc
	v_cndmask_b32_e64 v198, v37, 0, vcc
	s_waitcnt vmcnt(12)
	v_cndmask_b32_e64 v153, v61, 0, vcc
	v_cndmask_b32_e64 v163, v60, 0, vcc
	v_cndmask_b32_e64 v170, v59, 0, vcc
	v_cndmask_b32_e64 v177, v58, 0, vcc
	s_mov_b64 vcc, 0x3000
	s_waitcnt vmcnt(9)
	v_cndmask_b32_e64 v132, v52, 0, s[46:47]
	v_cndmask_b32_e64 v133, v53, 0, s[46:47]
	s_waitcnt vmcnt(8)
	v_cndmask_b32_e64 v91, v54, 0, s[50:51]
	v_cndmask_b32_e64 v186, v55, 0, s[50:51]
	s_waitcnt vmcnt(7)
	v_cndmask_b32_e64 v129, v42, 0, s[44:45]
	v_cndmask_b32_e64 v127, v43, 0, s[44:45]
	v_cndmask_b32_e64 v139, v44, 0, s[44:45]
	v_cndmask_b32_e64 v192, v45, 0, s[44:45]
	v_cndmask_b32_e64 v187, v56, 0, s[50:51]
	v_cndmask_b32_e64 v188, v57, 0, s[50:51]
	v_cndmask_b32_e64 v201, v26, 0, s[50:51]
	v_cndmask_b32_e64 v202, v27, 0, s[50:51]
	v_cndmask_b32_e64 v142, v32, 0, s[48:49]
	v_cndmask_b32_e64 v143, v33, 0, s[48:49]
	s_waitcnt vmcnt(5)
	v_cndmask_b32_e64 v154, v65, 0, s[52:53]
	v_cndmask_b32_e64 v164, v64, 0, s[52:53]
	v_cndmask_b32_e64 v171, v63, 0, s[52:53]
	v_cndmask_b32_e64 v178, v62, 0, s[52:53]
	s_lshl_b64 s[52:53], s[8:9], 2
	s_add_u32 s52, s80, s52
	s_addc_u32 s53, s81, s53
	v_lshl_add_u64 v[2:3], s[52:53], 0, v[0:1]
	global_load_dwordx4 v[52:55], v0, s[52:53] offset:16
	global_load_dwordx4 v[24:27], v0, s[52:53]
	v_lshl_add_u64 v[12:13], v[2:3], 0, vcc
	s_mov_b64 vcc, 0x6000
	s_waitcnt vmcnt(5)
	v_cndmask_b32_e64 v155, v69, 0, s[44:45]
	v_cndmask_b32_e64 v165, v68, 0, s[44:45]
	global_load_dwordx4 v[56:59], v[12:13], off offset:16
	v_cndmask_b32_e64 v172, v67, 0, s[44:45]
	v_lshl_add_u64 v[12:13], v[2:3], 0, vcc
	v_cndmask_b32_e64 v180, v66, 0, s[44:45]
	s_mov_b64 s[44:45], 0x9000
	global_load_dwordx4 v[60:63], v[12:13], off offset:16
	v_lshl_add_u64 v[12:13], v[2:3], 0, s[44:45]
	global_load_dwordx4 v[64:67], v[12:13], off offset:16
	s_movk_i32 s9, 0x3000
	v_add_co_u32_e32 v0, vcc, s9, v2
	s_movk_i32 s9, 0x6000
	s_nop 0
	v_addc_co_u32_e32 v1, vcc, 0, v3, vcc
	global_load_dwordx4 v[32:35], v[0:1], off
	v_add_co_u32_e32 v0, vcc, s9, v2
	s_mov_b32 s9, 0x9000
	s_nop 0
	v_addc_co_u32_e32 v1, vcc, 0, v3, vcc
	global_load_dwordx4 v[40:43], v[0:1], off
	v_add_co_u32_e32 v0, vcc, s9, v2
	v_cndmask_b32_e64 v138, v48, 0, s[42:43]
	s_nop 0
	v_addc_co_u32_e32 v1, vcc, 0, v3, vcc
	v_cndmask_b32_e64 v191, v49, 0, s[42:43]
	v_cndmask_b32_e64 v131, v50, 0, s[46:47]
	v_cndmask_b32_e64 v130, v51, 0, s[46:47]
	global_load_dwordx4 v[48:51], v[0:1], off
	v_cndmask_b32_e64 v203, v16, 0, s[48:49]
	v_cndmask_b32_e64 v204, v17, 0, s[48:49]
	v_lshlrev_b32_e32 v16, 16, v101
	v_and_b32_e32 v17, 0xffff0000, v101
	v_cndmask_b32_e64 v205, v18, 0, s[48:49]
	v_cndmask_b32_e64 v206, v19, 0, s[48:49]
	s_waitcnt vmcnt(9)
	v_cndmask_b32_e64 v175, v77, 0, s[48:49]
	v_cndmask_b32_e64 v184, v76, 0, s[48:49]
	v_lshlrev_b32_e32 v2, 16, v102
	v_and_b32_e32 v3, 0xffff0000, v102
	v_lshlrev_b32_e32 v18, 16, v103
	v_and_b32_e32 v19, 0xffff0000, v103
	v_lshlrev_b32_e32 v102, 16, v22
	v_and_b32_e32 v103, 0xffff0000, v22
	v_lshlrev_b32_e32 v76, 16, v23
	v_and_b32_e32 v77, 0xffff0000, v23
	v_lshlrev_b32_e32 v22, 16, v104
	v_and_b32_e32 v23, 0xffff0000, v104
	v_lshlrev_b32_e32 v104, 16, v105
	v_and_b32_e32 v105, 0xffff0000, v105
	v_cndmask_b32_e64 v158, v79, 0, s[48:49]
	v_cndmask_b32_e64 v168, v78, 0, s[48:49]
	v_lshlrev_b32_e32 v78, 16, v107
	v_and_b32_e32 v79, 0xffff0000, v107
	v_cndmask_b32_e64 v189, v30, 0, s[48:49]
	v_cndmask_b32_e64 v190, v31, 0, s[48:49]
	v_cmp_lt_i32_e32 vcc, v95, v160
	v_and_b32_e32 v107, 0xffff0000, v21
	s_waitcnt vmcnt(8)
	v_cndmask_b32_e64 v176, v81, 0, s[50:51]
	v_cndmask_b32_e32 v0, v159, v95, vcc
	v_cmp_lt_i32_e32 vcc, v144, v160
	v_cndmask_b32_e64 v182, v80, 0, s[50:51]
	v_lshlrev_b32_e32 v195, 2, v0
	v_cndmask_b32_e32 v0, v159, v144, vcc
	v_cmp_lt_i32_e32 vcc, v145, v160
	v_lshlrev_b32_e32 v80, 16, v111
	v_and_b32_e32 v81, 0xffff0000, v111
	v_lshlrev_b32_e32 v196, 2, v0
	v_cndmask_b32_e32 v0, v159, v145, vcc
	v_cmp_lt_i32_e32 vcc, v146, v160
	v_lshlrev_b32_e32 v197, 2, v0
	v_cndmask_b32_e64 v134, v46, 0, s[42:43]
	v_cndmask_b32_e32 v0, v159, v146, vcc
	v_lshlrev_b32_e32 v161, 2, v0
	s_waitcnt vmcnt(7)
	v_pk_fma_f32 v[16:17], v[52:53], v[16:17], 0 op_sel_hi:[1,1,0]
	v_ashrrev_i32_e32 v0, 5, v28
	v_cndmask_b32_e64 v136, v47, 0, s[42:43]
	v_lshlrev_b32_e32 v46, 16, v108
	v_and_b32_e32 v47, 0xffff0000, v108
	v_pk_fma_f32 v[2:3], v[54:55], v[2:3], 0 op_sel_hi:[1,1,0]
	s_waitcnt vmcnt(5)
	v_pk_fma_f32 v[16:17], v[56:57], v[22:23], v[16:17]
	v_lshlrev_b32_e32 v108, 16, v109
	v_and_b32_e32 v109, 0xffff0000, v109
	v_cndmask_b32_e64 v162, v83, 0, s[50:51]
	v_cndmask_b32_e64 v169, v82, 0, s[50:51]
	s_waitcnt vmcnt(4)
	v_pk_fma_f32 v[16:17], v[60:61], v[104:105], v[16:17]
	v_pk_fma_f32 v[2:3], v[58:59], v[18:19], v[2:3]
	s_waitcnt vmcnt(3)
	v_pk_fma_f32 v[30:31], v[64:65], v[78:79], v[16:17]
	v_lshlrev_b32_e32 v82, 16, v110
	v_mul_f32_e32 v16, 0xbfb8aa3b, v30
	v_exp_f32_e32 v16, v16
	v_mul_f32_e32 v17, 0xbfb8aa3b, v31
	v_exp_f32_e32 v17, v17
	v_and_b32_e32 v83, 0xffff0000, v110
	v_add_f32_e32 v16, 1.0, v16
	v_rcp_f32_e32 v36, v16
	v_add_f32_e32 v16, 1.0, v17
	v_rcp_f32_e32 v37, v16
	v_pk_fma_f32 v[18:19], v[54:55], v[18:19], 0 op_sel_hi:[1,1,0]
	v_or_b32_e32 v68, s8, v179
	v_pk_fma_f32 v[18:19], v[58:59], v[102:103], v[18:19]
	v_pk_mul_f32 v[118:119], v[30:31], v[36:37]
	v_lshlrev_b32_e32 v30, 16, v100
	v_and_b32_e32 v31, 0xffff0000, v100
	v_pk_fma_f32 v[30:31], v[26:27], v[30:31], 0 op_sel_hi:[1,1,0]
	v_lshlrev_b32_e32 v36, 16, v106
	v_and_b32_e32 v37, 0xffff0000, v106
	s_waitcnt vmcnt(2)
	v_pk_fma_f32 v[30:31], v[34:35], v[36:37], v[30:31]
	v_lshlrev_b32_e32 v106, 16, v21
	s_waitcnt vmcnt(1)
	v_pk_fma_f32 v[30:31], v[42:43], v[106:107], v[30:31]
	v_ashrrev_i32_e32 v69, 31, v68
	s_waitcnt vmcnt(0)
	v_pk_fma_f32 v[30:31], v[50:51], v[80:81], v[30:31]
	v_lshlrev_b32_e32 v116, 16, v112
	v_mul_f32_e32 v21, 0xbfb8aa3b, v30
	v_exp_f32_e32 v21, v21
	v_mul_f32_e32 v28, 0xbfb8aa3b, v31
	v_exp_f32_e32 v28, v28
	v_and_b32_e32 v117, 0xffff0000, v112
	v_add_f32_e32 v21, 1.0, v21
	v_rcp_f32_e32 v44, v21
	v_add_f32_e32 v21, 1.0, v28
	v_lshlrev_b32_e32 v28, 16, v29
	v_and_b32_e32 v29, 0xffff0000, v29
	v_pk_fma_f32 v[28:29], v[24:25], v[28:29], 0 op_sel_hi:[1,1,0]
	v_rcp_f32_e32 v45, v21
	v_pk_fma_f32 v[28:29], v[32:33], v[46:47], v[28:29]
	v_pk_fma_f32 v[18:19], v[62:63], v[76:77], v[18:19]
	v_pk_fma_f32 v[28:29], v[40:41], v[108:109], v[28:29]
	v_cndmask_b32_e64 v173, v9, 0, s[42:43]
	v_pk_fma_f32 v[28:29], v[48:49], v[82:83], v[28:29]
	v_cndmask_b32_e64 v181, v8, 0, s[42:43]
	v_mul_f32_e32 v21, 0xbfb8aa3b, v28
	v_lshl_add_u64 v[8:9], v[68:69], 2, s[80:81]
	v_exp_f32_e32 v21, v21
	v_mul_f32_e32 v69, 0xbfb8aa3b, v29
	v_pk_fma_f32 v[18:19], v[66:67], v[116:117], v[18:19]
	v_exp_f32_e32 v69, v69
	v_pk_mul_f32 v[120:121], v[30:31], v[44:45]
	v_mul_f32_e32 v31, 0xbfb8aa3b, v18
	v_exp_f32_e32 v44, v31
	v_mul_f32_e32 v31, 0xbfb8aa3b, v19
	v_exp_f32_e32 v45, v31
	v_add_f32_e32 v21, 1.0, v21
	v_rcp_f32_e32 v30, v21
	v_add_f32_e32 v21, 1.0, v69
	v_rcp_f32_e32 v31, v21
	v_add_f32_e32 v21, 1.0, v44
	v_rcp_f32_e32 v44, v21
	v_add_f32_e32 v21, 1.0, v45
	v_rcp_f32_e32 v45, v21
	v_lshlrev_b32_e32 v114, 16, v20
	v_and_b32_e32 v115, 0xffff0000, v20
	v_pk_mul_f32 v[208:209], v[28:29], v[30:31]
	v_pk_mul_f32 v[122:123], v[18:19], v[44:45]
	v_pk_fma_f32 v[18:19], v[52:53], v[22:23], 0 op_sel_hi:[1,1,0]
	v_pk_fma_f32 v[30:31], v[26:27], v[36:37], 0 op_sel_hi:[1,1,0]
	v_pk_fma_f32 v[18:19], v[56:57], v[104:105], v[18:19]
	v_pk_fma_f32 v[30:31], v[34:35], v[106:107], v[30:31]
	v_pk_fma_f32 v[18:19], v[60:61], v[78:79], v[18:19]
	v_lshlrev_b32_e32 v112, 16, v15
	v_pk_fma_f32 v[18:19], v[64:65], v[114:115], v[18:19]
	v_and_b32_e32 v113, 0xffff0000, v15
	v_mul_f32_e32 v20, 0xbfb8aa3b, v18
	v_exp_f32_e32 v22, v20
	v_mul_f32_e32 v20, 0xbfb8aa3b, v19
	v_exp_f32_e32 v23, v20
	v_pk_fma_f32 v[30:31], v[42:43], v[80:81], v[30:31]
	v_add_f32_e32 v22, 1.0, v22
	v_pk_fma_f32 v[30:31], v[50:51], v[112:113], v[30:31]
	v_add_f32_e32 v23, 1.0, v23
	v_mul_f32_e32 v15, 0xbfb8aa3b, v30
	v_exp_f32_e32 v15, v15
	v_rcp_f32_e32 v22, v22
	v_rcp_f32_e32 v23, v23
	v_lshlrev_b32_e32 v110, 16, v14
	v_add_f32_e32 v15, 1.0, v15
	v_and_b32_e32 v111, 0xffff0000, v14
	v_pk_mul_f32 v[124:125], v[18:19], v[22:23]
	v_rcp_f32_e32 v18, v15
	v_pk_fma_f32 v[14:15], v[24:25], v[46:47], 0 op_sel_hi:[1,1,0]
	v_mul_f32_e32 v36, 0xbfb8aa3b, v31
	v_pk_fma_f32 v[14:15], v[32:33], v[108:109], v[14:15]
	v_pk_fma_f32 v[2:3], v[62:63], v[102:103], v[2:3]
	v_pk_fma_f32 v[14:15], v[40:41], v[82:83], v[14:15]
	v_exp_f32_e32 v36, v36
	v_pk_fma_f32 v[14:15], v[48:49], v[110:111], v[14:15]
	v_cndmask_b32_e64 v156, v11, 0, s[42:43]
	v_mul_f32_e32 v22, 0xbfb8aa3b, v14
	v_mul_f32_e32 v23, 0xbfb8aa3b, v15
	v_exp_f32_e32 v22, v22
	v_exp_f32_e32 v23, v23
	v_cndmask_b32_e64 v166, v10, 0, s[42:43]
	v_pk_fma_f32 v[10:11], v[66:67], v[76:77], v[2:3]
	v_add_f32_e32 v22, 1.0, v22
	v_mul_f32_e32 v2, 0xbfb8aa3b, v10
	v_exp_f32_e32 v12, v2
	v_mul_f32_e32 v2, 0xbfb8aa3b, v11
	v_add_f32_e32 v23, 1.0, v23
	v_exp_f32_e32 v13, v2
	v_add_f32_e32 v19, 1.0, v36
	v_rcp_f32_e32 v22, v22
	v_rcp_f32_e32 v23, v23
	v_rcp_f32_e32 v19, v19
	v_add_f32_e32 v12, 1.0, v12
	v_add_f32_e32 v13, 1.0, v13
	v_pk_mul_f32 v[212:213], v[14:15], v[22:23]
	v_rcp_f32_e32 v12, v12
	v_rcp_f32_e32 v13, v13
	v_pk_mul_f32 v[28:29], v[208:209], v[208:209]
	v_pk_mul_f32 v[210:211], v[30:31], v[18:19]
	v_pk_mul_f32 v[14:15], v[212:213], v[212:213]
	v_pk_mul_f32 v[100:101], v[120:121], v[120:121]
	v_pk_mul_f32 v[18:19], v[210:211], v[210:211]
	v_mov_b32_e32 v22, v14
	v_mov_b32_e32 v23, v28
	v_mov_b32_e32 v28, v15
	v_pk_add_f32 v[14:15], v[22:23], v[28:29]
	v_mov_b32_e32 v22, v18
	v_mov_b32_e32 v23, v100
	v_pk_mul_f32 v[38:39], v[118:119], v[118:119]
	v_pk_mul_f32 v[36:37], v[124:125], v[124:125]
	v_pk_add_f32 v[14:15], v[22:23], v[14:15]
	v_mov_b32_e32 v100, v19
	v_pk_mul_f32 v[10:11], v[10:11], v[12:13]
	v_pk_add_f32 v[14:15], v[100:101], v[14:15]
	v_mov_b32_e32 v18, v36
	v_mov_b32_e32 v19, v38
	v_pk_mul_f32 v[12:13], v[10:11], v[10:11]
	v_pk_mul_f32 v[20:21], v[122:123], v[122:123]
	v_pk_add_f32 v[14:15], v[18:19], v[14:15]
	v_mov_b32_e32 v38, v37
	v_pk_add_f32 v[14:15], v[38:39], v[14:15]
	v_mov_b32_e32 v18, v20
	v_mov_b32_e32 v19, v12
	v_pk_add_f32 v[14:15], v[18:19], v[14:15]
	v_mov_b32_e32 v12, v21
	v_pk_add_f32 v[18:19], v[12:13], v[14:15]
	ds_bpermute_b32 v21, v195, v19
	ds_bpermute_b32 v20, v195, v18
	v_bitop3_b32 v0, v0, v152, 7 bitop3:0x78
	v_lshlrev_b32_e32 v1, 1, v75
	v_lshlrev_b32_e32 v0, 4, v0
	v_and_b32_e32 v1, 8, v1
	s_waitcnt lgkmcnt(0)
	v_pk_add_f32 v[20:21], v[18:19], v[20:21]
	v_add3_u32 v185, s19, v0, v1
	v_add_co_u32_e32 v0, vcc, s15, v8
	ds_bpermute_b32 v45, v196, v21
	ds_bpermute_b32 v44, v196, v20
	v_addc_co_u32_e32 v1, vcc, 0, v9, vcc
	v_add_co_u32_e32 v12, vcc, s83, v8
	v_cndmask_b32_e64 v174, v5, 0, s[46:47]
	v_cndmask_b32_e64 v183, v4, 0, s[46:47]
	v_lshl_add_u64 v[4:5], v[8:9], 0, s[28:29]
	v_lshl_add_u64 v[16:17], v[8:9], 0, s[36:37]
	v_addc_co_u32_e32 v13, vcc, 0, v9, vcc
	v_cndmask_b32_e64 v157, v7, 0, s[46:47]
	v_cndmask_b32_e64 v167, v6, 0, s[46:47]
	global_load_dwordx4 v[0:3], v[0:1], off
	s_nop 0
	global_load_dwordx4 v[4:7], v[4:5], off offset:16
	s_nop 0
	global_load_dwordx4 v[12:15], v[12:13], off
	s_nop 0
	global_load_dwordx4 v[28:31], v[16:17], off offset:16
	v_add_co_u32_e32 v16, vcc, s95, v8
	v_lshl_add_u64 v[22:23], v[8:9], 0, s[38:39]
	s_nop 0
	v_addc_co_u32_e32 v17, vcc, 0, v9, vcc
	s_waitcnt lgkmcnt(0)
	v_pk_add_f32 v[20:21], v[20:21], v[44:45]
	global_load_dwordx4 v[16:19], v[16:17], off
	s_nop 0
	global_load_dwordx4 v[36:39], v[22:23], off offset:16
	ds_bpermute_b32 v23, v197, v21
	ds_bpermute_b32 v22, v197, v20
	v_lshl_add_u64 v[46:47], v[8:9], 0, s[40:41]
	v_add_co_u32_e32 v8, vcc, s33, v8
	s_ashr_i32 s73, s72, 31
	s_waitcnt lgkmcnt(0)
	v_pk_add_f32 v[214:215], v[20:21], v[22:23]
	ds_bpermute_b32 v217, v161, v215
	ds_bpermute_b32 v216, v161, v214
	v_addc_co_u32_e32 v9, vcc, 0, v9, vcc
	global_load_dwordx4 v[20:23], v[8:9], off
	s_nop 0
	global_load_dwordx4 v[44:47], v[46:47], off offset:16
	s_lshl_b64 s[48:49], s[72:73], 14
	s_waitcnt lgkmcnt(0)
	v_pk_add_f32 v[8:9], v[214:215], v[216:217]
	s_add_u32 s8, s20, s48
	v_pk_add_f32 v[214:215], v[8:9], s[6:7] op_sel_hi:[1,0]
	s_addc_u32 s9, s21, s49
	v_mul_f32_e32 v8, 0x4b800000, v215
	v_cmp_gt_f32_e32 vcc, s12, v215
	v_mul_f32_e32 v69, 0x4b800000, v214
	v_ashrrev_i32_e32 v73, 31, v72
	v_cndmask_b32_e32 v8, v215, v8, vcc
	v_rsq_f32_e32 v8, v8
	v_lshl_add_u64 v[98:99], v[72:73], 1, s[8:9]
	s_add_u32 s8, s16, s48
	s_addc_u32 s9, s17, s49
	v_mul_f32_e32 v9, 0x45800000, v8
	v_cndmask_b32_e32 v8, v8, v9, vcc
	v_cmp_gt_f32_e32 vcc, s12, v214
	v_mul_f32_e32 v8, 0x3db504f3, v8
	v_pk_mul_f32 v[208:209], v[208:209], v[8:9] op_sel_hi:[1,0]
	v_cndmask_b32_e32 v69, v214, v69, vcc
	v_rsq_f32_e32 v69, v69
	v_pk_mul_f32 v[120:121], v[120:121], v[8:9] op_sel_hi:[1,0]
	v_lshl_add_u64 v[70:71], s[8:9], 0, v[84:85]
	v_mad_u64_u32 v[100:101], s[8:9], v72, s54, v[74:75]
	v_lshlrev_b32_e32 v72, 7, v72
	v_pk_mul_f32 v[218:219], v[118:119], v[8:9] op_sel_hi:[1,0]
	v_pk_mul_f32 v[220:221], v[10:11], v[8:9] op_sel_hi:[1,0]
	v_cvt_pk_bf16_f32 v9, v120, v121
	v_pk_mul_f32 v[118:119], v[86:87], v[208:209] op_sel_hi:[0,1]
	v_pk_mul_f32 v[120:121], v[86:87], v[120:121] op_sel_hi:[0,1]
	v_pk_fma_f32 v[102:103], v[54:55], v[102:103], 0 op_sel_hi:[1,1,0]
	v_ashrrev_i32_e32 v73, 31, v72
	v_cvt_pk_bf16_f32 v8, v208, v209
	v_cvt_pk_bf16_f32 v118, v118, v119
	v_cvt_pk_bf16_f32 v119, v120, v121
	v_pk_mul_f32 v[120:121], v[86:87], v[218:219] op_sel_hi:[0,1]
	v_pk_mul_f32 v[208:209], v[86:87], v[220:221] op_sel_hi:[0,1]
	v_pk_fma_f32 v[102:103], v[58:59], v[76:77], v[102:103]
	v_lshl_add_u64 v[216:217], v[72:73], 1, v[70:71]
	v_cvt_pk_bf16_f32 v120, v120, v121
	v_cvt_pk_bf16_f32 v121, v208, v209
	v_mul_f32_e32 v73, 0x45800000, v69
	v_lshlrev_b32_e32 v208, 16, v206
	v_and_b32_e32 v209, 0xffff0000, v206
	v_pk_fma_f32 v[102:103], v[62:63], v[116:117], v[102:103]
	v_cndmask_b32_e32 v69, v69, v73, vcc
	v_pk_fma_f32 v[102:103], v[66:67], v[208:209], v[102:103]
	v_mul_f32_e32 v84, 0x3db504f3, v69
	v_mul_f32_e32 v69, 0xbfb8aa3b, v102
	v_exp_f32_e32 v69, v69
	v_mul_f32_e32 v73, 0xbfb8aa3b, v103
	v_exp_f32_e32 v73, v73
	v_pk_fma_f32 v[104:105], v[52:53], v[104:105], 0 op_sel_hi:[1,1,0]
	global_store_dwordx4 v[216:217], v[118:121], off
	v_pk_fma_f32 v[104:105], v[56:57], v[78:79], v[104:105]
	v_add_f32_e32 v69, 1.0, v69
	v_pk_mul_f32 v[118:119], v[210:211], v[84:85] op_sel_hi:[1,0]
	v_lshlrev_b32_e32 v210, 16, v205
	v_and_b32_e32 v211, 0xffff0000, v205
	v_pk_fma_f32 v[104:105], v[60:61], v[114:115], v[104:105]
	v_rcp_f32_e32 v206, v69
	v_pk_fma_f32 v[104:105], v[64:65], v[210:211], v[104:105]
	v_add_f32_e32 v69, 1.0, v73
	v_mul_f32_e32 v73, 0xbfb8aa3b, v104
	v_exp_f32_e32 v73, v73
	v_mul_f32_e32 v101, 0xbfb8aa3b, v105
	v_exp_f32_e32 v101, v101
	v_rcp_f32_e32 v207, v69
	v_add_f32_e32 v69, 1.0, v73
	v_pk_mul_f32 v[120:121], v[212:213], v[84:85] op_sel_hi:[1,0]
	v_rcp_f32_e32 v212, v69
	v_add_f32_e32 v69, 1.0, v101
	v_rcp_f32_e32 v213, v69
	v_pk_fma_f32 v[106:107], v[26:27], v[106:107], 0 op_sel_hi:[1,1,0]
	v_pk_fma_f32 v[108:109], v[24:25], v[108:109], 0 op_sel_hi:[1,1,0]
	v_pk_fma_f32 v[106:107], v[34:35], v[80:81], v[106:107]
	v_pk_mul_f32 v[104:105], v[104:105], v[212:213]
	v_lshlrev_b32_e32 v212, 16, v204
	v_and_b32_e32 v213, 0xffff0000, v204
	v_pk_fma_f32 v[106:107], v[42:43], v[112:113], v[106:107]
	v_pk_fma_f32 v[108:109], v[32:33], v[82:83], v[108:109]
	v_pk_fma_f32 v[106:107], v[50:51], v[212:213], v[106:107]
	v_pk_fma_f32 v[54:55], v[54:55], v[76:77], 0 op_sel_hi:[1,1,0]
	v_mul_f32_e32 v69, 0xbfb8aa3b, v106
	v_exp_f32_e32 v69, v69
	v_mul_f32_e32 v73, 0xbfb8aa3b, v107
	v_exp_f32_e32 v73, v73
	v_lshlrev_b32_e32 v216, 16, v203
	v_add_f32_e32 v69, 1.0, v69
	v_and_b32_e32 v217, 0xffff0000, v203
	v_pk_fma_f32 v[108:109], v[40:41], v[110:111], v[108:109]
	v_pk_fma_f32 v[54:55], v[58:59], v[116:117], v[54:55]
	v_cvt_pk_bf16_f32 v10, v218, v219
	v_rcp_f32_e32 v214, v69
	v_add_f32_e32 v69, 1.0, v73
	v_pk_fma_f32 v[108:109], v[48:49], v[216:217], v[108:109]
	v_lshlrev_b32_e32 v218, 16, v202
	v_and_b32_e32 v219, 0xffff0000, v202
	v_pk_fma_f32 v[54:55], v[62:63], v[208:209], v[54:55]
	v_rcp_f32_e32 v215, v69
	v_mul_f32_e32 v69, 0xbfb8aa3b, v108
	v_pk_fma_f32 v[54:55], v[66:67], v[218:219], v[54:55]
	v_exp_f32_e32 v69, v69
	v_mul_f32_e32 v73, 0xbfb8aa3b, v109
	v_mul_f32_e32 v58, 0xbfb8aa3b, v54
	v_mul_f32_e32 v59, 0xbfb8aa3b, v55
	v_exp_f32_e32 v73, v73
	v_exp_f32_e32 v58, v58
	v_exp_f32_e32 v59, v59
	v_add_f32_e32 v69, 1.0, v69
	v_pk_mul_f32 v[106:107], v[106:107], v[214:215]
	v_rcp_f32_e32 v214, v69
	v_add_f32_e32 v69, 1.0, v73
	v_add_f32_e32 v58, 1.0, v58
	v_add_f32_e32 v59, 1.0, v59
	v_rcp_f32_e32 v215, v69
	v_rcp_f32_e32 v58, v58
	v_rcp_f32_e32 v59, v59
	v_pk_fma_f32 v[26:27], v[26:27], v[80:81], 0 op_sel_hi:[1,1,0]
	v_pk_fma_f32 v[24:25], v[24:25], v[82:83], 0 op_sel_hi:[1,1,0]
	v_pk_fma_f32 v[26:27], v[34:35], v[112:113], v[26:27]
	v_pk_mul_f32 v[66:67], v[108:109], v[214:215]
	v_pk_mul_f32 v[108:109], v[54:55], v[58:59]
	v_lshlrev_b32_e32 v58, 16, v200
	v_and_b32_e32 v59, 0xffff0000, v200
	v_pk_fma_f32 v[26:27], v[42:43], v[212:213], v[26:27]
	v_pk_fma_f32 v[24:25], v[32:33], v[110:111], v[24:25]
	v_pk_fma_f32 v[52:53], v[52:53], v[78:79], 0 op_sel_hi:[1,1,0]
	v_pk_fma_f32 v[26:27], v[50:51], v[58:59], v[26:27]
	v_lshlrev_b32_e32 v50, 16, v199
	v_and_b32_e32 v51, 0xffff0000, v199
	v_pk_fma_f32 v[24:25], v[40:41], v[216:217], v[24:25]
	v_pk_fma_f32 v[52:53], v[56:57], v[114:115], v[52:53]
	v_pk_fma_f32 v[24:25], v[48:49], v[50:51], v[24:25]
	v_lshlrev_b32_e32 v54, 16, v201
	v_and_b32_e32 v55, 0xffff0000, v201
	v_pk_fma_f32 v[52:53], v[60:61], v[210:211], v[52:53]
	v_mul_f32_e32 v34, 0xbfb8aa3b, v26
	v_mul_f32_e32 v32, 0xbfb8aa3b, v24
	v_mul_f32_e32 v33, 0xbfb8aa3b, v25
	v_pk_fma_f32 v[52:53], v[64:65], v[54:55], v[52:53]
	v_exp_f32_e32 v42, v34
	v_mul_f32_e32 v34, 0xbfb8aa3b, v27
	v_exp_f32_e32 v32, v32
	v_exp_f32_e32 v33, v33
	v_mul_f32_e32 v54, 0xbfb8aa3b, v52
	v_exp_f32_e32 v43, v34
	v_exp_f32_e32 v56, v54
	v_mul_f32_e32 v54, 0xbfb8aa3b, v53
	v_exp_f32_e32 v57, v54
	v_add_f32_e32 v32, 1.0, v32
	v_add_f32_e32 v33, 1.0, v33
	v_add_f32_e32 v42, 1.0, v42
	v_add_f32_e32 v43, 1.0, v43
	v_rcp_f32_e32 v32, v32
	v_rcp_f32_e32 v33, v33
	v_rcp_f32_e32 v42, v42
	v_rcp_f32_e32 v43, v43
	v_add_f32_e32 v56, 1.0, v56
	v_add_f32_e32 v57, 1.0, v57
	v_rcp_f32_e32 v56, v56
	v_rcp_f32_e32 v57, v57
	v_pk_mul_f32 v[32:33], v[24:25], v[32:33]
	v_pk_mul_f32 v[76:77], v[66:67], v[66:67]
	v_pk_mul_f32 v[42:43], v[26:27], v[42:43]
	v_pk_mul_f32 v[24:25], v[32:33], v[32:33]
	v_pk_mul_f32 v[62:63], v[106:107], v[106:107]
	v_pk_mul_f32 v[26:27], v[42:43], v[42:43]
	v_mov_b32_e32 v48, v24
	v_mov_b32_e32 v49, v76
	v_mov_b32_e32 v76, v25
	v_pk_mul_f32 v[34:35], v[52:53], v[56:57]
	v_pk_add_f32 v[24:25], v[48:49], v[76:77]
	v_mov_b32_e32 v48, v26
	v_mov_b32_e32 v49, v62
	v_pk_mul_f32 v[204:205], v[104:105], v[104:105]
	v_pk_mul_f32 v[40:41], v[34:35], v[34:35]
	v_pk_add_f32 v[24:25], v[48:49], v[24:25]
	v_mov_b32_e32 v62, v27
	v_pk_mul_f32 v[102:103], v[102:103], v[206:207]
	v_pk_add_f32 v[24:25], v[62:63], v[24:25]
	v_mov_b32_e32 v26, v40
	v_mov_b32_e32 v27, v204
	v_pk_mul_f32 v[206:207], v[102:103], v[102:103]
	v_pk_mul_f32 v[54:55], v[108:109], v[108:109]
	v_pk_add_f32 v[24:25], v[26:27], v[24:25]
	v_mov_b32_e32 v204, v41
	v_pk_add_f32 v[24:25], v[204:205], v[24:25]
	v_mov_b32_e32 v26, v54
	v_mov_b32_e32 v27, v206
	v_pk_add_f32 v[24:25], v[26:27], v[24:25]
	v_mov_b32_e32 v206, v55
	v_pk_add_f32 v[24:25], v[206:207], v[24:25]
	ds_bpermute_b32 v27, v195, v25
	ds_bpermute_b32 v26, v195, v24
	v_pk_mul_f32 v[48:49], v[94:95], v[118:119] op_sel_hi:[0,1]
	v_pk_mul_f32 v[124:125], v[124:125], v[84:85] op_sel_hi:[1,0]
	v_pk_mul_f32 v[122:123], v[122:123], v[84:85] op_sel_hi:[1,0]
	v_lshlrev_b32_e32 v80, 16, v192
	s_waitcnt lgkmcnt(0)
	v_pk_add_f32 v[26:27], v[24:25], v[26:27]
	ds_bpermute_b32 v41, v196, v27
	ds_bpermute_b32 v40, v196, v26
	v_pk_mul_f32 v[24:25], v[94:95], v[120:121] op_sel_hi:[0,1]
	v_cvt_pk_bf16_f32 v24, v24, v25
	v_cvt_pk_bf16_f32 v25, v48, v49
	v_pk_mul_f32 v[50:51], v[94:95], v[122:123] op_sel_hi:[0,1]
	s_waitcnt lgkmcnt(0)
	v_pk_add_f32 v[40:41], v[26:27], v[40:41]
	ds_bpermute_b32 v49, v197, v41
	ds_bpermute_b32 v48, v197, v40
	v_pk_mul_f32 v[26:27], v[94:95], v[124:125] op_sel_hi:[0,1]
	v_cvt_pk_bf16_f32 v26, v26, v27
	v_cvt_pk_bf16_f32 v27, v50, v51
	v_or_b32_e32 v50, 0x80, v72
	s_waitcnt lgkmcnt(0)
	v_pk_add_f32 v[40:41], v[40:41], v[48:49]
	ds_bpermute_b32 v49, v161, v41
	ds_bpermute_b32 v48, v161, v40
	v_ashrrev_i32_e32 v51, 31, v50
	v_lshl_add_u64 v[50:51], v[50:51], 1, v[70:71]
	global_store_dwordx4 v[50:51], v[24:27], off
	v_and_b32_e32 v81, 0xffff0000, v192
	v_cvt_pk_bf16_f32 v54, v124, v125
	s_waitcnt lgkmcnt(0)
	v_pk_add_f32 v[24:25], v[40:41], v[48:49]
	v_lshlrev_b32_e32 v124, 16, v139
	v_pk_add_f32 v[40:41], v[24:25], s[6:7] op_sel_hi:[1,0]
	v_and_b32_e32 v125, 0xffff0000, v139
	v_mul_f32_e32 v24, 0x4b800000, v41
	v_cmp_gt_f32_e32 vcc, s12, v41
	v_lshlrev_b32_e32 v112, 16, v136
	v_and_b32_e32 v113, 0xffff0000, v136
	v_cndmask_b32_e32 v24, v41, v24, vcc
	v_rsq_f32_e32 v26, v24
	v_or_b32_e32 v24, 0x100, v72
	v_ashrrev_i32_e32 v25, 31, v24
	v_lshl_add_u64 v[48:49], v[24:25], 1, v[70:71]
	v_mul_f32_e32 v24, 0x45800000, v26
	v_cndmask_b32_e32 v24, v26, v24, vcc
	v_mul_f32_e32 v24, 0x3db504f3, v24
	v_pk_mul_f32 v[26:27], v[66:67], v[24:25] op_sel_hi:[1,0]
	v_pk_mul_f32 v[50:51], v[106:107], v[24:25] op_sel_hi:[1,0]
	v_pk_mul_f32 v[60:61], v[104:105], v[24:25] op_sel_hi:[1,0]
	v_pk_mul_f32 v[62:63], v[102:103], v[24:25] op_sel_hi:[1,0]
	v_cvt_pk_bf16_f32 v56, v26, v27
	v_pk_mul_f32 v[24:25], v[90:91], v[26:27] op_sel_hi:[0,1]
	v_pk_mul_f32 v[26:27], v[90:91], v[50:51] op_sel_hi:[0,1]
	v_cvt_pk_bf16_f32 v24, v24, v25
	v_cvt_pk_bf16_f32 v25, v26, v27
	v_pk_mul_f32 v[26:27], v[90:91], v[60:61] op_sel_hi:[0,1]
	v_cvt_pk_bf16_f32 v26, v26, v27
	v_mul_f32_e32 v27, 0x4b800000, v40
	v_cmp_gt_f32_e32 vcc, s12, v40
	v_cvt_pk_bf16_f32 v57, v50, v51
	v_and_b32_e32 v51, 0xffff0000, v140
	v_cndmask_b32_e32 v27, v40, v27, vcc
	v_rsq_f32_e32 v50, v27
	v_pk_mul_f32 v[40:41], v[90:91], v[62:63] op_sel_hi:[0,1]
	v_cvt_pk_bf16_f32 v27, v40, v41
	global_store_dwordx4 v[48:49], v[24:27], off
	v_lshlrev_b32_e32 v48, 16, v141
	v_and_b32_e32 v49, 0xffff0000, v141
	v_mul_f32_e32 v24, 0x45800000, v50
	v_cndmask_b32_e32 v24, v50, v24, vcc
	v_mul_f32_e32 v24, 0x3db504f3, v24
	v_pk_mul_f32 v[26:27], v[32:33], v[24:25] op_sel_hi:[1,0]
	v_pk_mul_f32 v[32:33], v[42:43], v[24:25] op_sel_hi:[1,0]
	v_pk_mul_f32 v[34:35], v[34:35], v[24:25] op_sel_hi:[1,0]
	v_pk_mul_f32 v[40:41], v[108:109], v[24:25] op_sel_hi:[1,0]
	v_cvt_pk_bf16_f32 v64, v26, v27
	v_pk_mul_f32 v[24:25], v[96:97], v[26:27] op_sel_hi:[0,1]
	v_pk_mul_f32 v[26:27], v[96:97], v[32:33] op_sel_hi:[0,1]
	v_cvt_pk_bf16_f32 v66, v34, v35
	v_cvt_pk_bf16_f32 v24, v24, v25
	v_cvt_pk_bf16_f32 v25, v26, v27
	v_pk_mul_f32 v[26:27], v[96:97], v[34:35] op_sel_hi:[0,1]
	v_lshlrev_b32_e32 v34, 16, v198
	v_and_b32_e32 v35, 0xffff0000, v198
	v_cvt_pk_bf16_f32 v65, v32, v33
	v_cvt_pk_bf16_f32 v67, v40, v41
	v_pk_mul_f32 v[32:33], v[96:97], v[40:41] op_sel_hi:[0,1]
	s_waitcnt vmcnt(9)
	v_pk_fma_f32 v[34:35], v[6:7], v[34:35], 0 op_sel_hi:[1,1,0]
	v_lshlrev_b32_e32 v40, 16, v193
	v_and_b32_e32 v41, 0xffff0000, v193
	s_waitcnt vmcnt(7)
	v_pk_fma_f32 v[34:35], v[30:31], v[40:41], v[34:35]
	v_lshlrev_b32_e32 v108, 16, v191
	s_waitcnt vmcnt(5)
	v_pk_fma_f32 v[34:35], v[38:39], v[80:81], v[34:35]
	v_and_b32_e32 v109, 0xffff0000, v191
	s_waitcnt vmcnt(3)
	v_pk_fma_f32 v[34:35], v[46:47], v[108:109], v[34:35]
	v_cvt_pk_bf16_f32 v26, v26, v27
	v_mul_f32_e32 v42, 0xbfb8aa3b, v34
	v_mul_f32_e32 v43, 0xbfb8aa3b, v35
	v_cvt_pk_bf16_f32 v27, v32, v33
	v_or_b32_e32 v32, 3, v75
	v_exp_f32_e32 v42, v42
	v_exp_f32_e32 v43, v43
	v_mad_u64_u32 v[102:103], s[8:9], v32, s54, v[74:75]
	v_lshlrev_b32_e32 v32, 7, v32
	v_ashrrev_i32_e32 v33, 31, v32
	v_lshl_add_u64 v[32:33], v[32:33], 1, v[70:71]
	v_add_f32_e32 v42, 1.0, v42
	v_add_f32_e32 v43, 1.0, v43
	global_store_dwordx4 v[32:33], v[24:27], off
	v_rcp_f32_e32 v42, v42
	v_rcp_f32_e32 v43, v43
	v_lshlrev_b32_e32 v26, 16, v137
	v_and_b32_e32 v27, 0xffff0000, v137
	v_pk_fma_f32 v[26:27], v[2:3], v[26:27], 0 op_sel_hi:[1,1,0]
	v_lshlrev_b32_e32 v32, 16, v126
	v_and_b32_e32 v33, 0xffff0000, v126
	v_pk_fma_f32 v[48:49], v[4:5], v[48:49], 0 op_sel_hi:[1,1,0]
	v_lshlrev_b32_e32 v50, 16, v140
	v_pk_fma_f32 v[26:27], v[14:15], v[32:33], v[26:27]
	v_lshlrev_b32_e32 v126, 16, v127
	v_and_b32_e32 v127, 0xffff0000, v127
	v_pk_fma_f32 v[48:49], v[28:29], v[50:51], v[48:49]
	v_pk_fma_f32 v[26:27], v[18:19], v[126:127], v[26:27]
	v_pk_fma_f32 v[48:49], v[36:37], v[124:125], v[48:49]
	v_lshlrev_b32_e32 v110, 16, v138
	v_and_b32_e32 v111, 0xffff0000, v138
	v_pk_fma_f32 v[26:27], v[22:23], v[112:113], v[26:27]
	v_pk_fma_f32 v[48:49], v[44:45], v[110:111], v[48:49]
	v_pk_mul_f32 v[104:105], v[34:35], v[42:43]
	v_mul_f32_e32 v34, 0xbfb8aa3b, v26
	v_cvt_pk_bf16_f32 v58, v60, v61
	v_mul_f32_e32 v60, 0xbfb8aa3b, v48
	v_mul_f32_e32 v61, 0xbfb8aa3b, v49
	v_exp_f32_e32 v42, v34
	v_mul_f32_e32 v34, 0xbfb8aa3b, v27
	v_exp_f32_e32 v60, v60
	v_exp_f32_e32 v61, v61
	v_exp_f32_e32 v43, v34
	v_add_f32_e32 v42, 1.0, v42
	v_add_f32_e32 v60, 1.0, v60
	v_add_f32_e32 v61, 1.0, v61
	v_add_f32_e32 v43, 1.0, v43
	v_rcp_f32_e32 v60, v60
	v_rcp_f32_e32 v61, v61
	v_rcp_f32_e32 v42, v42
	v_rcp_f32_e32 v43, v43
	v_pk_fma_f32 v[40:41], v[6:7], v[40:41], 0 op_sel_hi:[1,1,0]
	v_lshlrev_b32_e32 v136, 16, v133
	v_pk_fma_f32 v[40:41], v[30:31], v[80:81], v[40:41]
	v_and_b32_e32 v137, 0xffff0000, v133
	v_pk_fma_f32 v[40:41], v[38:39], v[108:109], v[40:41]
	v_pk_mul_f32 v[82:83], v[48:49], v[60:61]
	v_pk_fma_f32 v[40:41], v[46:47], v[136:137], v[40:41]
	v_lshlrev_b32_e32 v48, 16, v135
	v_and_b32_e32 v49, 0xffff0000, v135
	v_pk_mul_f32 v[140:141], v[26:27], v[42:43]
	v_mul_f32_e32 v42, 0xbfb8aa3b, v40
	v_mul_f32_e32 v43, 0xbfb8aa3b, v41
	v_pk_fma_f32 v[48:49], v[0:1], v[48:49], 0 op_sel_hi:[1,1,0]
	v_lshlrev_b32_e32 v60, 16, v128
	v_and_b32_e32 v61, 0xffff0000, v128
	v_exp_f32_e32 v42, v42
	v_exp_f32_e32 v43, v43
	v_pk_fma_f32 v[48:49], v[12:13], v[60:61], v[48:49]
	v_lshlrev_b32_e32 v128, 16, v129
	v_and_b32_e32 v129, 0xffff0000, v129
	v_pk_fma_f32 v[48:49], v[16:17], v[128:129], v[48:49]
	v_lshlrev_b32_e32 v114, 16, v134
	v_and_b32_e32 v115, 0xffff0000, v134
	v_pk_fma_f32 v[48:49], v[20:21], v[114:115], v[48:49]
	v_cvt_pk_bf16_f32 v59, v62, v63
	v_mul_f32_e32 v62, 0xbfb8aa3b, v48
	v_mul_f32_e32 v63, 0xbfb8aa3b, v49
	v_add_f32_e32 v42, 1.0, v42
	v_add_f32_e32 v43, 1.0, v43
	v_exp_f32_e32 v62, v62
	v_exp_f32_e32 v63, v63
	v_rcp_f32_e32 v42, v42
	v_rcp_f32_e32 v43, v43
	v_add_f32_e32 v26, 1.0, v62
	v_add_f32_e32 v27, 1.0, v63
	v_rcp_f32_e32 v26, v26
	v_pk_mul_f32 v[106:107], v[40:41], v[42:43]
	v_pk_fma_f32 v[40:41], v[4:5], v[50:51], 0 op_sel_hi:[1,1,0]
	v_rcp_f32_e32 v27, v27
	v_pk_fma_f32 v[40:41], v[28:29], v[124:125], v[40:41]
	v_lshlrev_b32_e32 v134, 16, v132
	v_and_b32_e32 v135, 0xffff0000, v132
	v_pk_fma_f32 v[40:41], v[36:37], v[110:111], v[40:41]
	v_cvt_pk_bf16_f32 v52, v120, v121
	v_pk_fma_f32 v[40:41], v[44:45], v[134:135], v[40:41]
	v_pk_mul_f32 v[120:121], v[48:49], v[26:27]
	v_mul_f32_e32 v42, 0xbfb8aa3b, v40
	v_exp_f32_e32 v48, v42
	v_mul_f32_e32 v42, 0xbfb8aa3b, v41
	v_exp_f32_e32 v49, v42
	v_pk_fma_f32 v[32:33], v[2:3], v[32:33], 0 op_sel_hi:[1,1,0]
	v_add_f32_e32 v48, 1.0, v48
	v_rcp_f32_e32 v48, v48
	v_add_f32_e32 v49, 1.0, v49
	v_rcp_f32_e32 v49, v49
	v_pk_fma_f32 v[32:33], v[14:15], v[126:127], v[32:33]
	v_lshlrev_b32_e32 v132, 16, v130
	v_and_b32_e32 v133, 0xffff0000, v130
	v_pk_fma_f32 v[32:33], v[18:19], v[112:113], v[32:33]
	v_pk_mul_f32 v[116:117], v[40:41], v[48:49]
	v_pk_fma_f32 v[32:33], v[22:23], v[132:133], v[32:33]
	v_pk_fma_f32 v[48:49], v[0:1], v[60:61], 0 op_sel_hi:[1,1,0]
	v_mul_f32_e32 v50, 0xbfb8aa3b, v32
	v_mul_f32_e32 v51, 0xbfb8aa3b, v33
	v_exp_f32_e32 v50, v50
	v_exp_f32_e32 v51, v51
	v_pk_fma_f32 v[48:49], v[12:13], v[128:129], v[48:49]
	v_lshlrev_b32_e32 v130, 16, v131
	v_and_b32_e32 v131, 0xffff0000, v131
	v_pk_fma_f32 v[48:49], v[16:17], v[114:115], v[48:49]
	v_add_f32_e32 v40, 1.0, v50
	v_pk_fma_f32 v[48:49], v[20:21], v[130:131], v[48:49]
	v_add_f32_e32 v41, 1.0, v51
	v_mul_f32_e32 v50, 0xbfb8aa3b, v48
	v_mul_f32_e32 v51, 0xbfb8aa3b, v49
	v_exp_f32_e32 v50, v50
	v_exp_f32_e32 v51, v51
	v_rcp_f32_e32 v40, v40
	v_rcp_f32_e32 v41, v41
	v_add_f32_e32 v50, 1.0, v50
	v_add_f32_e32 v51, 1.0, v51
	v_rcp_f32_e32 v50, v50
	v_rcp_f32_e32 v51, v51
	v_cvt_pk_bf16_f32 v55, v122, v123
	v_cvt_pk_bf16_f32 v53, v118, v119
	v_pk_mul_f32 v[26:27], v[120:121], v[120:121]
	v_pk_mul_f32 v[122:123], v[48:49], v[50:51]
	v_pk_mul_f32 v[118:119], v[32:33], v[40:41]
	v_pk_mul_f32 v[40:41], v[122:123], v[122:123]
	v_pk_mul_f32 v[62:63], v[140:141], v[140:141]
	v_pk_mul_f32 v[32:33], v[118:119], v[118:119]
	v_mov_b32_e32 v48, v40
	v_mov_b32_e32 v49, v26
	v_mov_b32_e32 v26, v41
	v_pk_add_f32 v[26:27], v[48:49], v[26:27]
	v_mov_b32_e32 v40, v32
	v_mov_b32_e32 v41, v62
	v_pk_mul_f32 v[34:35], v[82:83], v[82:83]
	v_pk_mul_f32 v[60:61], v[116:117], v[116:117]
	v_pk_add_f32 v[26:27], v[40:41], v[26:27]
	v_mov_b32_e32 v62, v33
	v_pk_add_f32 v[26:27], v[62:63], v[26:27]
	v_mov_b32_e32 v32, v60
	v_mov_b32_e32 v33, v34
	v_pk_mul_f32 v[24:25], v[104:105], v[104:105]
	v_pk_mul_f32 v[42:43], v[106:107], v[106:107]
	v_pk_add_f32 v[26:27], v[32:33], v[26:27]
	v_mov_b32_e32 v34, v61
	v_pk_add_f32 v[26:27], v[34:35], v[26:27]
	v_mov_b32_e32 v32, v42
	v_mov_b32_e32 v33, v24
	v_pk_add_f32 v[26:27], v[32:33], v[26:27]
	v_mov_b32_e32 v24, v43
	v_pk_add_f32 v[24:25], v[24:25], v[26:27]
	ds_bpermute_b32 v27, v195, v25
	ds_bpermute_b32 v26, v195, v24
	v_add_u32_e32 v32, 0x400, v68
	v_ashrrev_i32_e32 v33, 31, v32
	v_lshl_add_u64 v[48:49], v[32:33], 2, s[80:81]
	v_pk_fma_f32 v[80:81], v[6:7], v[80:81], 0 op_sel_hi:[1,1,0]
	s_waitcnt lgkmcnt(0)
	v_pk_add_f32 v[34:35], v[24:25], v[26:27]
	ds_bpermute_b32 v41, v196, v35
	ds_bpermute_b32 v40, v196, v34
	v_add_co_u32_e32 v24, vcc, s15, v48
	v_pk_fma_f32 v[6:7], v[6:7], v[108:109], 0 op_sel_hi:[1,1,0]
	s_nop 0
	v_addc_co_u32_e32 v25, vcc, 0, v49, vcc
	s_waitcnt lgkmcnt(0)
	v_pk_add_f32 v[40:41], v[34:35], v[40:41]
	ds_bpermute_b32 v43, v197, v41
	ds_bpermute_b32 v42, v197, v40
	v_add_co_u32_e32 v34, vcc, s83, v48
	v_lshlrev_b32_e32 v192, 16, v143
	s_nop 0
	v_addc_co_u32_e32 v35, vcc, 0, v49, vcc
	s_waitcnt lgkmcnt(0)
	v_pk_add_f32 v[76:77], v[40:41], v[42:43]
	ds_bpermute_b32 v79, v161, v77
	ds_bpermute_b32 v78, v161, v76
	v_add_co_u32_e32 v40, vcc, s95, v48
	v_and_b32_e32 v193, 0xffff0000, v143
	v_pk_fma_f32 v[6:7], v[30:31], v[136:137], v[6:7]
	s_waitcnt lgkmcnt(0)
	v_pk_add_f32 v[76:77], v[76:77], v[78:79]
	v_addc_co_u32_e32 v41, vcc, 0, v49, vcc
	v_pk_add_f32 v[138:139], v[76:77], s[6:7] op_sel_hi:[1,0]
	v_lshlrev_b32_e32 v208, 16, v188
	v_and_b32_e32 v209, 0xffff0000, v188
	v_pk_fma_f32 v[6:7], v[38:39], v[192:193], v[6:7]
	v_mul_f32_e32 v76, 0x4b800000, v139
	v_cmp_gt_f32_e32 vcc, s12, v139
	v_pk_fma_f32 v[6:7], v[46:47], v[208:209], v[6:7]
	v_pk_fma_f32 v[80:81], v[30:31], v[108:109], v[80:81]
	v_cndmask_b32_e32 v76, v139, v76, vcc
	v_mul_f32_e32 v30, 0xbfb8aa3b, v6
	v_mul_f32_e32 v31, 0xbfb8aa3b, v7
	v_rsq_f32_e32 v84, v76
	v_exp_f32_e32 v30, v30
	v_exp_f32_e32 v31, v31
	v_pk_fma_f32 v[80:81], v[38:39], v[136:137], v[80:81]
	v_mul_f32_e32 v101, 0x45800000, v84
	v_pk_fma_f32 v[198:199], v[46:47], v[192:193], v[80:81]
	v_add_f32_e32 v30, 1.0, v30
	v_mul_f32_e32 v80, 0xbfb8aa3b, v198
	v_exp_f32_e32 v81, v80
	v_mul_f32_e32 v80, 0xbfb8aa3b, v199
	v_add_f32_e32 v31, 1.0, v31
	v_cndmask_b32_e32 v84, v84, v101, vcc
	v_exp_f32_e32 v101, v80
	v_pk_fma_f32 v[124:125], v[4:5], v[124:125], 0 op_sel_hi:[1,1,0]
	v_rcp_f32_e32 v30, v30
	v_rcp_f32_e32 v31, v31
	v_pk_fma_f32 v[124:125], v[28:29], v[110:111], v[124:125]
	v_lshlrev_b32_e32 v202, 16, v142
	v_and_b32_e32 v203, 0xffff0000, v142
	v_pk_fma_f32 v[124:125], v[36:37], v[134:135], v[124:125]
	v_pk_fma_f32 v[4:5], v[4:5], v[110:111], 0 op_sel_hi:[1,1,0]
	v_add_f32_e32 v81, 1.0, v81
	v_pk_fma_f32 v[142:143], v[44:45], v[202:203], v[124:125]
	v_pk_fma_f32 v[4:5], v[28:29], v[134:135], v[4:5]
	v_rcp_f32_e32 v200, v81
	v_add_f32_e32 v81, 1.0, v101
	v_mul_f32_e32 v101, 0xbfb8aa3b, v142
	v_pk_mul_f32 v[30:31], v[6:7], v[30:31]
	v_lshlrev_b32_e32 v6, 16, v187
	v_and_b32_e32 v7, 0xffff0000, v187
	v_pk_fma_f32 v[4:5], v[36:37], v[202:203], v[4:5]
	v_exp_f32_e32 v101, v101
	v_mul_f32_e32 v103, 0xbfb8aa3b, v143
	v_rcp_f32_e32 v201, v81
	v_pk_fma_f32 v[4:5], v[44:45], v[6:7], v[4:5]
	v_exp_f32_e32 v103, v103
	v_mul_f32_e32 v6, 0xbfb8aa3b, v4
	v_pk_fma_f32 v[126:127], v[2:3], v[126:127], 0 op_sel_hi:[1,1,0]
	v_exp_f32_e32 v28, v6
	v_mul_f32_e32 v6, 0xbfb8aa3b, v5
	v_pk_fma_f32 v[126:127], v[14:15], v[112:113], v[126:127]
	v_exp_f32_e32 v29, v6
	v_pk_fma_f32 v[2:3], v[2:3], v[112:113], 0 op_sel_hi:[1,1,0]
	v_add_f32_e32 v81, 1.0, v101
	v_pk_mul_f32 v[124:125], v[140:141], v[84:85] op_sel_hi:[1,0]
	v_pk_mul_f32 v[140:141], v[198:199], v[200:201]
	v_lshlrev_b32_e32 v200, 16, v190
	v_and_b32_e32 v201, 0xffff0000, v190
	v_pk_fma_f32 v[126:127], v[18:19], v[132:133], v[126:127]
	v_pk_fma_f32 v[2:3], v[14:15], v[132:133], v[2:3]
	v_rcp_f32_e32 v204, v81
	v_add_f32_e32 v81, 1.0, v103
	v_pk_fma_f32 v[126:127], v[22:23], v[200:201], v[126:127]
	v_lshlrev_b32_e32 v36, 16, v186
	v_and_b32_e32 v37, 0xffff0000, v186
	v_pk_fma_f32 v[2:3], v[18:19], v[200:201], v[2:3]
	v_rcp_f32_e32 v205, v81
	v_mul_f32_e32 v81, 0xbfb8aa3b, v126
	v_pk_fma_f32 v[2:3], v[22:23], v[36:37], v[2:3]
	v_exp_f32_e32 v81, v81
	v_mul_f32_e32 v101, 0xbfb8aa3b, v127
	v_add_f32_e32 v28, 1.0, v28
	v_add_f32_e32 v29, 1.0, v29
	v_mul_f32_e32 v14, 0xbfb8aa3b, v2
	v_mul_f32_e32 v15, 0xbfb8aa3b, v3
	v_exp_f32_e32 v101, v101
	v_rcp_f32_e32 v28, v28
	v_rcp_f32_e32 v29, v29
	v_exp_f32_e32 v14, v14
	v_exp_f32_e32 v15, v15
	v_pk_fma_f32 v[128:129], v[0:1], v[128:129], 0 op_sel_hi:[1,1,0]
	v_pk_fma_f32 v[0:1], v[0:1], v[114:115], 0 op_sel_hi:[1,1,0]
	v_pk_fma_f32 v[128:129], v[12:13], v[114:115], v[128:129]
	v_add_f32_e32 v81, 1.0, v81
	v_lshlrev_b32_e32 v206, 16, v189
	v_and_b32_e32 v207, 0xffff0000, v189
	v_pk_fma_f32 v[128:129], v[16:17], v[130:131], v[128:129]
	v_pk_fma_f32 v[0:1], v[12:13], v[130:131], v[0:1]
	v_pk_mul_f32 v[142:143], v[142:143], v[204:205]
	v_rcp_f32_e32 v204, v81
	v_add_f32_e32 v81, 1.0, v101
	v_pk_fma_f32 v[128:129], v[20:21], v[206:207], v[128:129]
	v_pk_mul_f32 v[22:23], v[4:5], v[28:29]
	v_add_f32_e32 v4, 1.0, v14
	v_add_f32_e32 v5, 1.0, v15
	v_lshlrev_b32_e32 v14, 16, v91
	v_and_b32_e32 v15, 0xffff0000, v91
	v_pk_fma_f32 v[0:1], v[16:17], v[206:207], v[0:1]
	v_rcp_f32_e32 v205, v81
	v_mul_f32_e32 v81, 0xbfb8aa3b, v128
	v_pk_fma_f32 v[0:1], v[20:21], v[14:15], v[0:1]
	v_exp_f32_e32 v81, v81
	v_mul_f32_e32 v101, 0xbfb8aa3b, v129
	v_mul_f32_e32 v12, 0xbfb8aa3b, v0
	v_mul_f32_e32 v13, 0xbfb8aa3b, v1
	v_exp_f32_e32 v101, v101
	v_exp_f32_e32 v12, v12
	v_exp_f32_e32 v13, v13
	v_add_f32_e32 v81, 1.0, v81
	v_pk_mul_f32 v[126:127], v[126:127], v[204:205]
	v_rcp_f32_e32 v204, v81
	v_add_f32_e32 v81, 1.0, v101
	v_add_f32_e32 v12, 1.0, v12
	v_add_f32_e32 v13, 1.0, v13
	v_rcp_f32_e32 v205, v81
	v_rcp_f32_e32 v12, v12
	v_rcp_f32_e32 v13, v13
	v_rcp_f32_e32 v4, v4
	v_rcp_f32_e32 v5, v5
	v_pk_mul_f32 v[46:47], v[128:129], v[204:205]
	v_pk_mul_f32 v[0:1], v[0:1], v[12:13]
	v_pk_mul_f32 v[108:109], v[46:47], v[46:47]
	v_pk_mul_f32 v[2:3], v[2:3], v[4:5]
	v_pk_mul_f32 v[12:13], v[0:1], v[0:1]
	v_pk_mul_f32 v[38:39], v[126:127], v[126:127]
	v_pk_mul_f32 v[4:5], v[2:3], v[2:3]
	v_mov_b32_e32 v16, v12
	v_mov_b32_e32 v17, v108
	v_mov_b32_e32 v108, v13
	v_pk_add_f32 v[12:13], v[16:17], v[108:109]
	v_mov_b32_e32 v16, v4
	v_mov_b32_e32 v17, v38
	v_pk_mul_f32 v[190:191], v[142:143], v[142:143]
	v_pk_mul_f32 v[14:15], v[22:23], v[22:23]
	v_pk_add_f32 v[12:13], v[16:17], v[12:13]
	v_mov_b32_e32 v38, v5
	v_pk_add_f32 v[4:5], v[38:39], v[12:13]
	v_mov_b32_e32 v12, v14
	v_mov_b32_e32 v13, v190
	v_pk_mul_f32 v[198:199], v[140:141], v[140:141]
	v_pk_mul_f32 v[6:7], v[30:31], v[30:31]
	v_pk_add_f32 v[4:5], v[12:13], v[4:5]
	v_mov_b32_e32 v190, v15
	v_pk_add_f32 v[4:5], v[190:191], v[4:5]
	v_mov_b32_e32 v12, v6
	v_mov_b32_e32 v13, v198
	v_pk_add_f32 v[4:5], v[12:13], v[4:5]
	v_mov_b32_e32 v198, v7
	v_pk_add_f32 v[12:13], v[198:199], v[4:5]
	ds_bpermute_b32 v15, v195, v13
	ds_bpermute_b32 v14, v195, v12
	v_lshl_add_u64 v[32:33], v[48:49], 0, s[28:29]
	global_load_dwordx4 v[60:63], v[24:25], off
	s_nop 0
	global_load_dwordx4 v[24:27], v[32:33], off offset:16
	v_lshl_add_u64 v[32:33], v[48:49], 0, s[36:37]
	v_lshl_add_u64 v[50:51], v[48:49], 0, s[38:39]
	s_waitcnt lgkmcnt(0)
	v_pk_add_f32 v[12:13], v[12:13], v[14:15]
	ds_bpermute_b32 v15, v196, v13
	ds_bpermute_b32 v14, v196, v12
	global_load_dwordx4 v[68:71], v[34:35], off
	s_nop 0
	global_load_dwordx4 v[32:35], v[32:33], off offset:16
	s_nop 0
	global_load_dwordx4 v[72:75], v[40:41], off
	s_nop 0
	global_load_dwordx4 v[40:43], v[50:51], off offset:16
	v_lshl_add_u64 v[50:51], v[48:49], 0, s[40:41]
	v_add_co_u32_e64 v48, s[42:43], s33, v48
	v_mul_f32_e32 v16, 0x4b800000, v138
	s_nop 0
	v_addc_co_u32_e64 v49, s[42:43], 0, v49, s[42:43]
	global_load_dwordx4 v[76:79], v[48:49], off
	s_nop 0
	global_load_dwordx4 v[48:51], v[50:51], off offset:16
	v_cmp_gt_f32_e32 vcc, s12, v138
	s_waitcnt lgkmcnt(0)
	v_pk_add_f32 v[12:13], v[12:13], v[14:15]
	ds_bpermute_b32 v15, v197, v13
	v_cndmask_b32_e32 v16, v138, v16, vcc
	ds_bpermute_b32 v14, v197, v12
	v_rsq_f32_e32 v16, v16
	v_pk_mul_f32 v[4:5], v[104:105], v[84:85] op_sel_hi:[1,0]
	v_pk_mul_f32 v[120:121], v[120:121], v[84:85] op_sel_hi:[1,0]
	v_pk_mul_f32 v[6:7], v[82:83], v[84:85] op_sel_hi:[1,0]
	v_mul_f32_e32 v17, 0x45800000, v16
	s_waitcnt lgkmcnt(0)
	v_pk_add_f32 v[12:13], v[12:13], v[14:15]
	v_cndmask_b32_e32 v18, v16, v17, vcc
	ds_bpermute_b32 v17, v161, v13
	ds_bpermute_b32 v16, v161, v12
	v_pk_mul_f32 v[28:29], v[122:123], v[18:19] op_sel_hi:[1,0]
	v_pk_mul_f32 v[44:45], v[118:119], v[18:19] op_sel_hi:[1,0]
	v_pk_mul_f32 v[104:105], v[116:117], v[18:19] op_sel_hi:[1,0]
	v_cvt_pk_bf16_f32 v11, v220, v221
	s_waitcnt lgkmcnt(0)
	v_pk_add_f32 v[12:13], v[12:13], v[16:17]
	v_cvt_pk_bf16_f32 v80, v120, v121
	v_pk_add_f32 v[20:21], v[12:13], s[6:7] op_sel_hi:[1,0]
	v_cvt_pk_bf16_f32 v81, v124, v125
	v_mul_f32_e32 v12, 0x4b800000, v21
	v_cmp_gt_f32_e32 vcc, s12, v21
	v_cvt_pk_bf16_f32 v82, v6, v7
	v_cvt_pk_bf16_f32 v83, v4, v5
	v_cndmask_b32_e32 v12, v21, v12, vcc
	v_rsq_f32_e32 v19, v12
	v_mul_f32_e32 v21, 0x4b800000, v20
	v_cvt_pk_bf16_f32 v14, v28, v29
	v_cvt_pk_bf16_f32 v15, v44, v45
	v_pk_mul_f32 v[12:13], v[106:107], v[18:19] op_sel_hi:[1,0]
	v_mul_f32_e32 v18, 0x45800000, v19
	v_cndmask_b32_e32 v36, v19, v18, vcc
	v_cmp_gt_f32_e32 vcc, s12, v20
	v_pk_mul_f32 v[46:47], v[46:47], v[36:37] op_sel_hi:[1,0]
	v_pk_mul_f32 v[106:107], v[126:127], v[36:37] op_sel_hi:[1,0]
	v_cndmask_b32_e32 v20, v20, v21, vcc
	v_pk_mul_f32 v[108:109], v[142:143], v[36:37] op_sel_hi:[1,0]
	v_rsq_f32_e32 v37, v20
	v_cvt_pk_bf16_f32 v16, v104, v105
	v_cvt_pk_bf16_f32 v17, v12, v13
	v_cvt_pk_bf16_f32 v18, v46, v47
	v_pk_mul_f32 v[110:111], v[140:141], v[36:37] op_sel_hi:[1,0]
	v_mul_f32_e32 v36, 0x45800000, v37
	v_cndmask_b32_e32 v84, v37, v36, vcc
	v_pk_mul_f32 v[112:113], v[0:1], v[84:85] op_sel_hi:[1,0]
	v_pk_mul_f32 v[114:115], v[2:3], v[84:85] op_sel_hi:[1,0]
	ds_read_b128 v[0:3], v87 offset:256
	v_pk_mul_f32 v[22:23], v[22:23], v[84:85] op_sel_hi:[1,0]
	v_pk_mul_f32 v[30:31], v[30:31], v[84:85] op_sel_hi:[1,0]
	v_cvt_pk_bf16_f32 v19, v106, v107
	v_cvt_pk_bf16_f32 v20, v108, v109
	v_cvt_pk_bf16_f32 v21, v110, v111
	v_cvt_pk_bf16_f32 v36, v112, v113
	v_cvt_pk_bf16_f32 v37, v114, v115
	v_cvt_pk_bf16_f32 v38, v22, v23
	v_cvt_pk_bf16_f32 v39, v30, v31
	v_mov_b32_e32 v116, v120
	v_mov_b32_e32 v117, v28
	ds_write_b128 v100, v[8:11] offset:17408
	ds_write_b128 v100, v[52:55] offset:17680
	ds_write_b128 v100, v[56:59] offset:17952
	ds_write_b128 v102, v[64:67] offset:17408
	ds_write_b128 v100, v[80:83]
	ds_write_b128 v100, v[14:17] offset:272
	ds_write_b128 v100, v[18:21] offset:544
	ds_write_b128 v102, v[36:39]
	v_mov_b32_e32 v8, v46
	v_mov_b32_e32 v9, v112
	s_waitcnt lgkmcnt(8)
	v_pk_mul_f32 v[118:119], v[0:1], v[116:117]
	v_mov_b32_e32 v87, v94
	v_pk_mul_f32 v[10:11], v[2:3], v[8:9]
	v_mov_b32_e32 v91, v96
	v_pk_mul_f32 v[118:119], v[86:87], v[118:119]
	v_pk_mul_f32 v[10:11], v[90:91], v[10:11]
	v_cvt_pk_bf16_f32 v118, v118, v119
	v_cvt_pk_bf16_f32 v119, v10, v11
	v_pk_mul_f32 v[10:11], v[88:89], v[116:117]
	v_pk_mul_f32 v[8:9], v[92:93], v[8:9]
	v_lshlrev_b32_e32 v84, 10, v151
	v_cvt_pk_bf16_f32 v10, v10, v11
	v_cvt_pk_bf16_f32 v11, v8, v9
	v_lshl_add_u64 v[8:9], v[98:99], 0, v[84:85]
	v_mov_b32_e32 v28, v121
	v_mov_b32_e32 v112, v47
	global_store_dwordx2 v[8:9], v[10:11], off
	v_pk_mul_f32 v[8:9], v[0:1], v[28:29]
	v_pk_mul_f32 v[10:11], v[2:3], v[112:113]
	v_pk_mul_f32 v[8:9], v[86:87], v[8:9]
	v_pk_mul_f32 v[10:11], v[90:91], v[10:11]
	v_or_b32_e32 v16, 1, v179
	v_cvt_pk_bf16_f32 v8, v8, v9
	v_cvt_pk_bf16_f32 v9, v10, v11
	v_pk_mul_f32 v[10:11], v[88:89], v[28:29]
	v_pk_mul_f32 v[14:15], v[92:93], v[112:113]
	v_cvt_pk_bf16_f32 v10, v10, v11
	v_cvt_pk_bf16_f32 v11, v14, v15
	v_lshlrev_b32_e32 v14, 7, v16
	v_mov_b32_e32 v15, v85
	v_lshl_add_u64 v[14:15], v[98:99], 0, v[14:15]
	v_mad_u32_u24 v21, v16, s13, v185
	global_store_dwordx2 v[14:15], v[10:11], off
	v_mov_b32_e32 v10, v124
	v_mov_b32_e32 v11, v44
	v_mov_b32_e32 v16, v106
	v_mov_b32_e32 v17, v114
	v_pk_mul_f32 v[14:15], v[0:1], v[10:11]
	v_pk_mul_f32 v[18:19], v[2:3], v[16:17]
	s_movk_i32 s8, 0x480
	v_pk_mul_f32 v[14:15], v[86:87], v[14:15]
	v_pk_mul_f32 v[18:19], v[90:91], v[18:19]
	v_mad_u32_u24 v20, v151, s8, v185
	v_cvt_pk_bf16_f32 v14, v14, v15
	v_cvt_pk_bf16_f32 v15, v18, v19
	v_add_u32_e32 v28, 0x8800, v21
	ds_write_b64 v20, v[118:119] offset:34816
	v_pk_mul_f32 v[10:11], v[88:89], v[10:11]
	v_pk_mul_f32 v[16:17], v[92:93], v[16:17]
	ds_write2_b64 v28, v[8:9], v[14:15] offset1:18
	v_or_b32_e32 v8, 0x100, v84
	v_mov_b32_e32 v9, v85
	v_cvt_pk_bf16_f32 v10, v10, v11
	v_cvt_pk_bf16_f32 v11, v16, v17
	v_lshl_add_u64 v[8:9], v[98:99], 0, v[8:9]
	v_mov_b32_e32 v44, v125
	v_mov_b32_e32 v114, v107
	global_store_dwordx2 v[8:9], v[10:11], off
	v_pk_mul_f32 v[8:9], v[0:1], v[44:45]
	v_pk_mul_f32 v[10:11], v[2:3], v[114:115]
	v_pk_mul_f32 v[8:9], v[86:87], v[8:9]
	v_pk_mul_f32 v[10:11], v[90:91], v[10:11]
	v_cvt_pk_bf16_f32 v8, v8, v9
	v_cvt_pk_bf16_f32 v9, v10, v11
	v_pk_mul_f32 v[10:11], v[88:89], v[44:45]
	v_pk_mul_f32 v[14:15], v[92:93], v[114:115]
	v_cvt_pk_bf16_f32 v10, v10, v11
	v_cvt_pk_bf16_f32 v11, v14, v15
	v_or_b32_e32 v14, 0x180, v84
	v_mov_b32_e32 v15, v85
	v_lshl_add_u64 v[14:15], v[98:99], 0, v[14:15]
	global_store_dwordx2 v[14:15], v[10:11], off
	v_mov_b32_e32 v10, v6
	v_mov_b32_e32 v11, v104
	v_mov_b32_e32 v16, v108
	v_mov_b32_e32 v17, v22
	v_pk_mul_f32 v[14:15], v[0:1], v[10:11]
	v_pk_mul_f32 v[18:19], v[2:3], v[16:17]
	v_pk_mul_f32 v[14:15], v[86:87], v[14:15]
	v_pk_mul_f32 v[18:19], v[90:91], v[18:19]
	v_cvt_pk_bf16_f32 v14, v14, v15
	v_cvt_pk_bf16_f32 v15, v18, v19
	v_pk_mul_f32 v[10:11], v[88:89], v[10:11]
	v_pk_mul_f32 v[16:17], v[92:93], v[16:17]
	ds_write2_b64 v28, v[8:9], v[14:15] offset0:36 offset1:54
	v_or_b32_e32 v8, 0x200, v84
	v_mov_b32_e32 v9, v85
	v_cvt_pk_bf16_f32 v10, v10, v11
	v_cvt_pk_bf16_f32 v11, v16, v17
	v_lshl_add_u64 v[8:9], v[98:99], 0, v[8:9]
	v_mov_b32_e32 v104, v7
	v_mov_b32_e32 v22, v109
	global_store_dwordx2 v[8:9], v[10:11], off
	v_pk_mul_f32 v[6:7], v[0:1], v[104:105]
	v_pk_mul_f32 v[8:9], v[2:3], v[22:23]
	v_pk_mul_f32 v[6:7], v[86:87], v[6:7]
	v_pk_mul_f32 v[8:9], v[90:91], v[8:9]
	v_cvt_pk_bf16_f32 v6, v6, v7
	v_cvt_pk_bf16_f32 v7, v8, v9
	v_pk_mul_f32 v[8:9], v[88:89], v[104:105]
	v_pk_mul_f32 v[10:11], v[92:93], v[22:23]
	v_cvt_pk_bf16_f32 v8, v8, v9
	v_cvt_pk_bf16_f32 v9, v10, v11
	v_or_b32_e32 v10, 0x280, v84
	v_mov_b32_e32 v11, v85
	v_lshl_add_u64 v[10:11], v[98:99], 0, v[10:11]
	global_store_dwordx2 v[10:11], v[8:9], off
	v_mov_b32_e32 v8, v4
	v_mov_b32_e32 v9, v12
	v_mov_b32_e32 v14, v110
	v_mov_b32_e32 v15, v30
	v_pk_mul_f32 v[10:11], v[0:1], v[8:9]
	v_pk_mul_f32 v[16:17], v[2:3], v[14:15]
	v_pk_mul_f32 v[10:11], v[86:87], v[10:11]
	v_pk_mul_f32 v[16:17], v[90:91], v[16:17]
	v_cvt_pk_bf16_f32 v10, v10, v11
	v_cvt_pk_bf16_f32 v11, v16, v17
	v_pk_mul_f32 v[8:9], v[88:89], v[8:9]
	v_pk_mul_f32 v[14:15], v[92:93], v[14:15]
	ds_write2_b64 v28, v[6:7], v[10:11] offset0:72 offset1:90
	v_or_b32_e32 v6, 0x300, v84
	v_mov_b32_e32 v7, v85
	v_cvt_pk_bf16_f32 v8, v8, v9
	v_cvt_pk_bf16_f32 v9, v14, v15
	v_lshl_add_u64 v[6:7], v[98:99], 0, v[6:7]
	v_mov_b32_e32 v12, v5
	v_mov_b32_e32 v30, v111
	global_store_dwordx2 v[6:7], v[8:9], off
	v_pk_mul_f32 v[4:5], v[0:1], v[12:13]
	v_pk_mul_f32 v[6:7], v[2:3], v[30:31]
	v_pk_mul_f32 v[4:5], v[86:87], v[4:5]
	v_pk_mul_f32 v[6:7], v[90:91], v[6:7]
	v_cvt_pk_bf16_f32 v4, v4, v5
	v_cvt_pk_bf16_f32 v5, v6, v7
	v_pk_mul_f32 v[6:7], v[88:89], v[12:13]
	v_pk_mul_f32 v[8:9], v[92:93], v[30:31]
	v_lshlrev_b32_e32 v11, 16, v181
	v_lshlrev_b32_e32 v10, 16, v180
	v_cvt_pk_bf16_f32 v6, v6, v7
	v_cvt_pk_bf16_f32 v7, v8, v9
	v_lshlrev_b32_e32 v9, 16, v183
	v_mov_b32_e32 v8, v11
	s_waitcnt vmcnt(14)
	v_pk_fma_f32 v[14:15], v[60:61], v[10:11], 0 op_sel_hi:[0,1,0]
	ds_write_b64 v21, v[4:5] offset:35680
	v_lshlrev_b32_e32 v5, 16, v184
	v_mov_b32_e32 v4, v9
	s_waitcnt vmcnt(12)
	v_pk_fma_f32 v[14:15], v[68:69], v[8:9], v[14:15] op_sel_hi:[0,1,1]
	v_lshlrev_b32_e32 v13, 16, v182
	v_mov_b32_e32 v12, v5
	s_waitcnt vmcnt(10)
	v_pk_fma_f32 v[4:5], v[72:73], v[4:5], v[14:15] op_sel_hi:[0,1,1]
	s_waitcnt vmcnt(8)
	v_pk_fma_f32 v[4:5], v[76:77], v[12:13], v[4:5] op_sel_hi:[0,1,1]
	v_mul_f32_e32 v12, 0xbfb8aa3b, v5
	v_exp_f32_e32 v12, v12
	v_mul_f32_e32 v13, 0xbfb8aa3b, v4
	v_exp_f32_e32 v14, v13
	v_lshlrev_b32_e32 v15, 16, v178
	v_add_f32_e32 v12, 1.0, v12
	v_rcp_f32_e32 v13, v12
	v_add_f32_e32 v12, 1.0, v14
	v_lshlrev_b32_e32 v14, 16, v177
	v_pk_fma_f32 v[16:17], v[60:61], v[14:15], 0 op_sel_hi:[0,1,0]
	v_pk_mov_b32 v[14:15], v[14:15], v[10:11] op_sel:[1,0]
	v_rcp_f32_e32 v12, v12
	v_pk_fma_f32 v[14:15], v[68:69], v[14:15], v[16:17] op_sel_hi:[0,1,1]
	v_pk_fma_f32 v[10:11], v[72:73], v[10:11], v[14:15] op_sel_hi:[0,1,1]
	v_pk_fma_f32 v[8:9], v[76:77], v[8:9], v[10:11] op_sel_hi:[0,1,1]
	v_mul_f32_e32 v10, 0xbfb8aa3b, v9
	v_exp_f32_e32 v10, v10
	v_mul_f32_e32 v11, 0xbfb8aa3b, v8
	v_exp_f32_e32 v14, v11
	v_or_b32_e32 v84, 0x380, v84
	v_add_f32_e32 v10, 1.0, v10
	v_rcp_f32_e32 v11, v10
	v_add_f32_e32 v10, 1.0, v14
	v_rcp_f32_e32 v10, v10
	v_lshl_add_u64 v[14:15], v[98:99], 0, v[84:85]
	global_store_dwordx2 v[14:15], v[6:7], off
	v_pk_mul_f32 v[4:5], v[4:5], v[12:13]
	v_pk_mul_f32 v[6:7], v[8:9], v[10:11]
	v_and_b32_e32 v10, 0xffff0000, v181
	v_and_b32_e32 v8, 0xffff0000, v183
	v_and_b32_e32 v12, 0xffff0000, v180
	v_mov_b32_e32 v13, v10
	v_mov_b32_e32 v11, v8
	v_pk_fma_f32 v[16:17], v[60:61], v[12:13], 0 op_sel:[1,0,0] op_sel_hi:[1,1,0]
	v_and_b32_e32 v9, 0xffff0000, v184
	v_pk_fma_f32 v[16:17], v[68:69], v[10:11], v[16:17] op_sel:[1,0,0]
	v_and_b32_e32 v15, 0xffff0000, v182
	v_mov_b32_e32 v14, v9
	v_pk_fma_f32 v[8:9], v[72:73], v[8:9], v[16:17] op_sel:[1,0,0]
	v_pk_mul_f32 v[6:7], v[0:1], v[6:7]
	v_pk_fma_f32 v[8:9], v[76:77], v[14:15], v[8:9] op_sel:[1,0,0]
	v_cvt_pk_bf16_f32 v6, v6, v7
	v_mul_f32_e32 v14, 0xbfb8aa3b, v9
	v_exp_f32_e32 v14, v14
	v_mul_f32_e32 v15, 0xbfb8aa3b, v8
	v_exp_f32_e32 v16, v15
	v_and_b32_e32 v17, 0xffff0000, v178
	v_add_f32_e32 v7, 1.0, v14
	v_rcp_f32_e32 v15, v7
	v_add_f32_e32 v7, 1.0, v16
	v_and_b32_e32 v16, 0xffff0000, v177
	v_pk_fma_f32 v[18:19], v[60:61], v[16:17], 0 op_sel:[1,0,0] op_sel_hi:[1,1,0]
	v_pk_mov_b32 v[16:17], v[16:17], v[12:13] op_sel:[1,0]
	v_rcp_f32_e32 v14, v7
	v_pk_fma_f32 v[16:17], v[68:69], v[16:17], v[18:19] op_sel:[1,0,0]
	v_pk_mul_f32 v[4:5], v[2:3], v[4:5]
	v_pk_fma_f32 v[12:13], v[72:73], v[12:13], v[16:17] op_sel:[1,0,0]
	v_add_u32_e32 v30, 0xd000, v20
	v_pk_fma_f32 v[10:11], v[76:77], v[10:11], v[12:13] op_sel:[1,0,0]
	v_mov_b32_e32 v22, v63
	v_mul_f32_e32 v12, 0xbfb8aa3b, v11
	v_exp_f32_e32 v12, v12
	v_mul_f32_e32 v13, 0xbfb8aa3b, v10
	v_exp_f32_e32 v16, v13
	v_mov_b32_e32 v20, v71
	v_add_f32_e32 v7, 1.0, v12
	v_rcp_f32_e32 v13, v7
	v_add_f32_e32 v7, 1.0, v16
	v_rcp_f32_e32 v12, v7
	v_cvt_pk_bf16_f32 v7, v4, v5
	v_pk_mul_f32 v[4:5], v[8:9], v[14:15]
	v_lshlrev_b32_e32 v15, 16, v173
	v_pk_mul_f32 v[8:9], v[10:11], v[12:13]
	v_lshlrev_b32_e32 v12, 16, v174
	v_lshlrev_b32_e32 v14, 16, v172
	v_lshlrev_b32_e32 v10, 16, v175
	v_mov_b32_e32 v16, v15
	v_mov_b32_e32 v17, v12
	v_pk_fma_f32 v[18:19], v[62:63], v[14:15], 0 op_sel_hi:[0,1,0]
	v_mov_b32_e32 v13, v10
	v_pk_fma_f32 v[18:19], v[70:71], v[16:17], v[18:19] op_sel_hi:[0,1,1]
	v_lshlrev_b32_e32 v11, 16, v176
	v_pk_fma_f32 v[12:13], v[74:75], v[12:13], v[18:19] op_sel_hi:[0,1,1]
	v_pk_mul_f32 v[8:9], v[0:1], v[8:9]
	v_pk_fma_f32 v[10:11], v[78:79], v[10:11], v[12:13] op_sel_hi:[0,1,1]
	v_cvt_pk_bf16_f32 v8, v8, v9
	v_mul_f32_e32 v9, 0xbfb8aa3b, v11
	v_exp_f32_e32 v12, v9
	v_mul_f32_e32 v9, 0xbfb8aa3b, v10
	v_exp_f32_e32 v13, v9
	v_pk_mul_f32 v[4:5], v[2:3], v[4:5]
	s_nop 0
	v_cvt_pk_bf16_f32 v9, v4, v5
	v_add_f32_e32 v4, 1.0, v12
	v_rcp_f32_e32 v5, v4
	v_add_f32_e32 v4, 1.0, v13
	v_lshlrev_b32_e32 v13, 16, v171
	v_lshlrev_b32_e32 v12, 16, v170
	v_pk_fma_f32 v[18:19], v[62:63], v[12:13], 0 op_sel_hi:[0,1,0]
	v_pk_mov_b32 v[12:13], v[12:13], v[14:15] op_sel:[1,0]
	v_rcp_f32_e32 v4, v4
	v_pk_fma_f32 v[12:13], v[70:71], v[12:13], v[18:19] op_sel_hi:[0,1,1]
	v_pk_fma_f32 v[12:13], v[74:75], v[14:15], v[12:13] op_sel_hi:[0,1,1]
	v_pk_fma_f32 v[12:13], v[78:79], v[16:17], v[12:13] op_sel_hi:[0,1,1]
	v_mul_f32_e32 v14, 0xbfb8aa3b, v13
	v_exp_f32_e32 v14, v14
	v_mul_f32_e32 v15, 0xbfb8aa3b, v12
	v_exp_f32_e32 v16, v15
	ds_write2_b64 v30, v[6:7], v[8:9] offset1:18
	v_add_f32_e32 v14, 1.0, v14
	v_rcp_f32_e32 v15, v14
	v_add_f32_e32 v14, 1.0, v16
	v_rcp_f32_e32 v14, v14
	v_pk_mul_f32 v[4:5], v[10:11], v[4:5]
	v_and_b32_e32 v10, 0xffff0000, v174
	v_and_b32_e32 v8, 0xffff0000, v175
	v_pk_mul_f32 v[6:7], v[12:13], v[14:15]
	v_and_b32_e32 v12, 0xffff0000, v173
	v_and_b32_e32 v14, 0xffff0000, v172
	v_mov_b32_e32 v15, v12
	v_mov_b32_e32 v13, v10
	v_pk_fma_f32 v[28:29], v[22:23], v[14:15], 0 op_sel_hi:[0,1,0]
	v_mov_b32_e32 v11, v8
	v_mov_b32_e32 v18, v75
	v_pk_fma_f32 v[28:29], v[20:21], v[12:13], v[28:29] op_sel_hi:[0,1,1]
	v_and_b32_e32 v9, 0xffff0000, v176
	v_mov_b32_e32 v16, v79
	v_pk_fma_f32 v[10:11], v[18:19], v[10:11], v[28:29] op_sel_hi:[0,1,1]
	v_pk_fma_f32 v[8:9], v[16:17], v[8:9], v[10:11] op_sel_hi:[0,1,1]
	v_mul_f32_e32 v11, 0xbfb8aa3b, v8
	v_mul_f32_e32 v10, 0xbfb8aa3b, v9
	v_exp_f32_e32 v17, v11
	v_and_b32_e32 v29, 0xffff0000, v171
	v_and_b32_e32 v28, 0xffff0000, v170
	v_exp_f32_e32 v10, v10
	v_pk_fma_f32 v[22:23], v[22:23], v[28:29], 0 op_sel_hi:[0,1,0]
	v_pk_mov_b32 v[28:29], v[28:29], v[14:15] op_sel:[1,0]
	v_pk_mul_f32 v[6:7], v[0:1], v[6:7]
	v_pk_fma_f32 v[20:21], v[20:21], v[28:29], v[22:23] op_sel_hi:[0,1,1]
	v_pk_fma_f32 v[14:15], v[18:19], v[14:15], v[20:21] op_sel_hi:[0,1,1]
	v_pk_fma_f32 v[12:13], v[16:17], v[12:13], v[14:15] op_sel_hi:[0,1,1]
	v_cvt_pk_bf16_f32 v6, v6, v7
	v_add_f32_e32 v7, 1.0, v10
	v_mul_f32_e32 v10, 0xbfb8aa3b, v13
	v_exp_f32_e32 v14, v10
	v_mul_f32_e32 v10, 0xbfb8aa3b, v12
	v_exp_f32_e32 v16, v10
	v_rcp_f32_e32 v11, v7
	v_add_f32_e32 v7, 1.0, v17
	v_rcp_f32_e32 v10, v7
	v_add_f32_e32 v7, 1.0, v14
	v_rcp_f32_e32 v15, v7
	v_add_f32_e32 v7, 1.0, v16
	v_rcp_f32_e32 v14, v7
	v_pk_mul_f32 v[4:5], v[2:3], v[4:5]
	v_mov_b32_e32 v22, v27
	v_cvt_pk_bf16_f32 v7, v4, v5
	v_pk_mul_f32 v[4:5], v[8:9], v[10:11]
	v_pk_mul_f32 v[8:9], v[12:13], v[14:15]
	v_lshlrev_b32_e32 v12, 16, v167
	v_lshlrev_b32_e32 v15, 16, v166
	v_lshlrev_b32_e32 v14, 16, v165
	v_lshlrev_b32_e32 v10, 16, v168
	v_mov_b32_e32 v16, v15
	v_mov_b32_e32 v17, v12
	v_pk_fma_f32 v[18:19], v[24:25], v[14:15], 0 op_sel_hi:[0,1,0]
	v_mov_b32_e32 v13, v10
	v_pk_fma_f32 v[18:19], v[32:33], v[16:17], v[18:19] op_sel_hi:[0,1,1]
	v_lshlrev_b32_e32 v11, 16, v169
	v_pk_fma_f32 v[12:13], v[40:41], v[12:13], v[18:19] op_sel_hi:[0,1,1]
	v_pk_mul_f32 v[8:9], v[0:1], v[8:9]
	s_waitcnt vmcnt(8)
	v_pk_fma_f32 v[10:11], v[48:49], v[10:11], v[12:13] op_sel_hi:[0,1,1]
	v_cvt_pk_bf16_f32 v8, v8, v9
	v_mul_f32_e32 v9, 0xbfb8aa3b, v11
	v_exp_f32_e32 v9, v9
	v_mul_f32_e32 v12, 0xbfb8aa3b, v10
	v_lshlrev_b32_e32 v19, 16, v164
	v_lshlrev_b32_e32 v18, 16, v163
	v_exp_f32_e32 v12, v12
	v_pk_fma_f32 v[20:21], v[24:25], v[18:19], 0 op_sel_hi:[0,1,0]
	v_pk_mov_b32 v[18:19], v[18:19], v[14:15] op_sel:[1,0]
	v_add_f32_e32 v9, 1.0, v9
	v_pk_fma_f32 v[18:19], v[32:33], v[18:19], v[20:21] op_sel_hi:[0,1,1]
	v_pk_fma_f32 v[14:15], v[40:41], v[14:15], v[18:19] op_sel_hi:[0,1,1]
	v_pk_fma_f32 v[14:15], v[48:49], v[16:17], v[14:15] op_sel_hi:[0,1,1]
	v_rcp_f32_e32 v13, v9
	v_add_f32_e32 v9, 1.0, v12
	v_mul_f32_e32 v12, 0xbfb8aa3b, v15
	v_exp_f32_e32 v16, v12
	v_mul_f32_e32 v12, 0xbfb8aa3b, v14
	v_exp_f32_e32 v18, v12
	v_rcp_f32_e32 v12, v9
	v_add_f32_e32 v9, 1.0, v16
	v_rcp_f32_e32 v17, v9
	v_add_f32_e32 v9, 1.0, v18
	v_rcp_f32_e32 v16, v9
	v_pk_mul_f32 v[4:5], v[2:3], v[4:5]
	s_nop 0
	v_cvt_pk_bf16_f32 v9, v4, v5
	v_pk_mul_f32 v[4:5], v[10:11], v[12:13]
	v_and_b32_e32 v12, 0xffff0000, v166
	ds_write2_b64 v30, v[6:7], v[8:9] offset0:36 offset1:54
	v_pk_mul_f32 v[6:7], v[14:15], v[16:17]
	v_and_b32_e32 v10, 0xffff0000, v167
	v_and_b32_e32 v14, 0xffff0000, v165
	v_mov_b32_e32 v15, v12
	v_and_b32_e32 v8, 0xffff0000, v168
	v_mov_b32_e32 v13, v10
	v_pk_fma_f32 v[16:17], v[24:25], v[14:15], 0 op_sel:[1,0,0] op_sel_hi:[1,1,0]
	v_mov_b32_e32 v11, v8
	v_pk_fma_f32 v[16:17], v[32:33], v[12:13], v[16:17] op_sel:[1,0,0]
	v_and_b32_e32 v9, 0xffff0000, v169
	v_pk_fma_f32 v[10:11], v[40:41], v[10:11], v[16:17] op_sel:[1,0,0]
	v_pk_mul_f32 v[6:7], v[0:1], v[6:7]
	v_pk_fma_f32 v[8:9], v[48:49], v[8:9], v[10:11] op_sel:[1,0,0]
	v_cvt_pk_bf16_f32 v6, v6, v7
	v_mul_f32_e32 v10, 0xbfb8aa3b, v9
	v_exp_f32_e32 v10, v10
	v_mul_f32_e32 v11, 0xbfb8aa3b, v8
	v_exp_f32_e32 v16, v11
	v_and_b32_e32 v17, 0xffff0000, v164
	v_add_f32_e32 v7, 1.0, v10
	v_rcp_f32_e32 v11, v7
	v_add_f32_e32 v7, 1.0, v16
	v_and_b32_e32 v16, 0xffff0000, v163
	v_pk_fma_f32 v[18:19], v[24:25], v[16:17], 0 op_sel:[1,0,0] op_sel_hi:[1,1,0]
	v_pk_mov_b32 v[16:17], v[16:17], v[14:15] op_sel:[1,0]
	v_pk_mul_f32 v[4:5], v[2:3], v[4:5]
	v_pk_fma_f32 v[16:17], v[32:33], v[16:17], v[18:19] op_sel:[1,0,0]
	s_nop 0
	v_pk_fma_f32 v[14:15], v[40:41], v[14:15], v[16:17] op_sel:[1,0,0]
	s_nop 0
	v_pk_fma_f32 v[12:13], v[48:49], v[12:13], v[14:15] op_sel:[1,0,0]
	s_nop 0
	v_mul_f32_e32 v10, 0xbfb8aa3b, v13
	v_exp_f32_e32 v14, v10
	v_mul_f32_e32 v10, 0xbfb8aa3b, v12
	v_exp_f32_e32 v16, v10
	v_rcp_f32_e32 v10, v7
	v_add_f32_e32 v7, 1.0, v14
	v_rcp_f32_e32 v15, v7
	v_add_f32_e32 v7, 1.0, v16
	v_rcp_f32_e32 v14, v7
	v_cvt_pk_bf16_f32 v7, v4, v5
	v_pk_mul_f32 v[4:5], v[8:9], v[10:11]
	v_lshlrev_b32_e32 v10, 16, v158
	v_pk_mul_f32 v[8:9], v[12:13], v[14:15]
	v_lshlrev_b32_e32 v12, 16, v157
	v_lshlrev_b32_e32 v15, 16, v156
	v_lshlrev_b32_e32 v14, 16, v155
	v_mov_b32_e32 v16, v15
	v_mov_b32_e32 v17, v12
	v_pk_fma_f32 v[18:19], v[26:27], v[14:15], 0 op_sel_hi:[0,1,0]
	v_mov_b32_e32 v13, v10
	v_pk_fma_f32 v[18:19], v[34:35], v[16:17], v[18:19] op_sel_hi:[0,1,1]
	v_lshlrev_b32_e32 v11, 16, v162
	v_pk_fma_f32 v[12:13], v[42:43], v[12:13], v[18:19] op_sel_hi:[0,1,1]
	v_pk_mul_f32 v[8:9], v[0:1], v[8:9]
	v_pk_fma_f32 v[10:11], v[50:51], v[10:11], v[12:13] op_sel_hi:[0,1,1]
	v_cvt_pk_bf16_f32 v8, v8, v9
	v_mul_f32_e32 v9, 0xbfb8aa3b, v11
	v_exp_f32_e32 v9, v9
	v_mul_f32_e32 v12, 0xbfb8aa3b, v10
	v_lshlrev_b32_e32 v19, 16, v154
	v_lshlrev_b32_e32 v18, 16, v153
	v_exp_f32_e32 v12, v12
	v_pk_fma_f32 v[20:21], v[26:27], v[18:19], 0 op_sel_hi:[0,1,0]
	v_pk_mov_b32 v[18:19], v[18:19], v[14:15] op_sel:[1,0]
	v_add_f32_e32 v9, 1.0, v9
	v_pk_fma_f32 v[18:19], v[34:35], v[18:19], v[20:21] op_sel_hi:[0,1,1]
	v_pk_fma_f32 v[14:15], v[42:43], v[14:15], v[18:19] op_sel_hi:[0,1,1]
	v_pk_fma_f32 v[14:15], v[50:51], v[16:17], v[14:15] op_sel_hi:[0,1,1]
	v_rcp_f32_e32 v13, v9
	v_add_f32_e32 v9, 1.0, v12
	v_mul_f32_e32 v12, 0xbfb8aa3b, v15
	v_exp_f32_e32 v16, v12
	v_mul_f32_e32 v12, 0xbfb8aa3b, v14
	v_exp_f32_e32 v18, v12
	v_rcp_f32_e32 v12, v9
	v_add_f32_e32 v9, 1.0, v16
	v_rcp_f32_e32 v17, v9
	v_add_f32_e32 v9, 1.0, v18
	v_rcp_f32_e32 v16, v9
	v_pk_mul_f32 v[4:5], v[2:3], v[4:5]
	v_mov_b32_e32 v20, v35
	v_cvt_pk_bf16_f32 v9, v4, v5
	v_pk_mul_f32 v[4:5], v[10:11], v[12:13]
	v_and_b32_e32 v12, 0xffff0000, v156
	ds_write2_b64 v30, v[6:7], v[8:9] offset0:72 offset1:90
	v_pk_mul_f32 v[6:7], v[14:15], v[16:17]
	v_and_b32_e32 v10, 0xffff0000, v157
	v_and_b32_e32 v14, 0xffff0000, v155
	v_mov_b32_e32 v15, v12
	v_and_b32_e32 v8, 0xffff0000, v158
	v_mov_b32_e32 v13, v10
	v_pk_fma_f32 v[24:25], v[22:23], v[14:15], 0 op_sel_hi:[0,1,0]
	v_mov_b32_e32 v11, v8
	v_mov_b32_e32 v18, v43
	v_pk_fma_f32 v[24:25], v[20:21], v[12:13], v[24:25] op_sel_hi:[0,1,1]
	v_and_b32_e32 v9, 0xffff0000, v162
	v_mov_b32_e32 v16, v51
	v_pk_fma_f32 v[10:11], v[18:19], v[10:11], v[24:25] op_sel_hi:[0,1,1]
	v_pk_fma_f32 v[8:9], v[16:17], v[8:9], v[10:11] op_sel_hi:[0,1,1]
	v_mul_f32_e32 v11, 0xbfb8aa3b, v8
	v_mul_f32_e32 v10, 0xbfb8aa3b, v9
	v_exp_f32_e32 v17, v11
	v_and_b32_e32 v25, 0xffff0000, v154
	v_and_b32_e32 v24, 0xffff0000, v153
	v_exp_f32_e32 v10, v10
	v_pk_fma_f32 v[22:23], v[22:23], v[24:25], 0 op_sel_hi:[0,1,0]
	v_pk_mov_b32 v[24:25], v[24:25], v[14:15] op_sel:[1,0]
	v_pk_mul_f32 v[6:7], v[0:1], v[6:7]
	v_pk_fma_f32 v[20:21], v[20:21], v[24:25], v[22:23] op_sel_hi:[0,1,1]
	v_pk_fma_f32 v[14:15], v[18:19], v[14:15], v[20:21] op_sel_hi:[0,1,1]
	v_pk_fma_f32 v[12:13], v[16:17], v[12:13], v[14:15] op_sel_hi:[0,1,1]
	v_cvt_pk_bf16_f32 v6, v6, v7
	v_add_f32_e32 v7, 1.0, v10
	v_mul_f32_e32 v10, 0xbfb8aa3b, v13
	v_exp_f32_e32 v14, v10
	v_mul_f32_e32 v10, 0xbfb8aa3b, v12
	v_exp_f32_e32 v16, v10
	v_rcp_f32_e32 v11, v7
	v_add_f32_e32 v7, 1.0, v17
	v_rcp_f32_e32 v10, v7
	v_add_f32_e32 v7, 1.0, v14
	v_rcp_f32_e32 v15, v7
	v_add_f32_e32 v7, 1.0, v16
	v_rcp_f32_e32 v14, v7
	v_pk_mul_f32 v[4:5], v[2:3], v[4:5]
	v_and_b32_e32 v24, -16, v152
	v_cvt_pk_bf16_f32 v7, v4, v5
	v_pk_mul_f32 v[4:5], v[8:9], v[10:11]
	v_pk_mul_f32 v[8:9], v[12:13], v[14:15]
	v_pk_mul_f32 v[2:3], v[2:3], v[4:5]
	v_pk_mul_f32 v[0:1], v[0:1], v[8:9]
	v_add_u32_e32 v26, s19, v24
	v_cvt_pk_bf16_f32 v0, v0, v1
	v_cvt_pk_bf16_f32 v1, v2, v3
	v_mad_u32_u24 v29, v151, s54, v26
	ds_write2_b64 v30, v[6:7], v[0:1] offset0:108 offset1:126
	s_waitcnt lgkmcnt(0)
	s_barrier
	ds_read_b128 v[12:15], v29
	v_or_b32_e32 v27, s10, v151
	v_mad_u32_u24 v0, v27, s54, v148
	v_add_u32_e32 v25, v0, v24
	ds_read_b128 v[4:7], v25 offset:17408
	ds_read_b128 v[16:19], v29 offset:64
	ds_read_b128 v[8:11], v25 offset:17472
	v_lshl_add_u32 v20, v27, 2, s76
	ds_read_b128 v[0:3], v25 offset:17600
	ds_read_b32 v28, v20
	s_waitcnt lgkmcnt(4)
	v_mfma_f32_16x16x32_bf16 v[20:23], v[12:15], v[4:7], 0
	ds_read_b128 v[30:33], v29 offset:128
	ds_read_b128 v[12:15], v25 offset:17536
	ds_read_b128 v[34:37], v29 offset:192
	s_waitcnt lgkmcnt(5)
	v_mfma_f32_16x16x32_bf16 v[16:19], v[16:19], v[8:11], v[20:23]
	s_waitcnt lgkmcnt(1)
	v_mfma_f32_16x16x32_bf16 v[16:19], v[30:33], v[12:15], v[16:19]
	v_ashrrev_i32_e32 v32, 4, v152
	v_lshlrev_b32_e32 v20, 2, v32
	v_ashrrev_i32_e32 v21, 31, v20
	s_waitcnt lgkmcnt(0)
	v_mfma_f32_16x16x32_bf16 v[16:19], v[34:37], v[0:3], v[16:19]
	v_cmp_le_i32_e32 vcc, v20, v27
	v_lshl_add_u32 v29, v20, 2, s76
	v_mov_b32_e32 v30, 0
	s_and_saveexec_b64 s[8:9], vcc
	s_cbranch_execz .LBB0_230
	ds_read_b32 v22, v29
	s_waitcnt lgkmcnt(0)
	v_sub_f32_e32 v22, v28, v22
	v_mul_f32_e32 v22, 0x3fb8aa3b, v22
	v_exp_f32_e32 v22, v22
	s_nop 0
	v_mul_f32_e32 v30, v16, v22

.LBB0_304:
	s_cmpk_eq_i32 s85, 0x200
	s_cselect_b64 s[8:9], -1, 0
	s_or_b64 s[8:9], s[30:31], s[8:9]
	s_and_b64 vcc, exec, s[8:9]
	s_waitcnt lgkmcnt(0)
	s_barrier
	s_cbranch_vccnz .LBB0_226
	s_and_b32 s8, s84, 0xfffff800
	s_lshl_b32 s9, s84, 3
	s_and_b32 s9, s9, 0x7c0
	s_or_b32 s8, s8, s9
	v_mbcnt_lo_u32_b32 v0, -1, 0
	v_mbcnt_hi_u32_b32 v0, -1, v0
	s_mov_b32 s42, 0xbfb8aa3b
	v_add_u32_e32 v2, s8, v0
	v_ashrrev_i32_e32 v3, 31, v2
	v_readlane_b32 s8, v241, 17
	v_lshlrev_b64 v[2:3], 6, v[2:3]
	v_readlane_b32 s9, v241, 18
	s_mov_b32 s43, 0x42ce8ed0
	s_mov_b32 s44, 0xc2b17218
	v_lshl_add_u64 v[2:3], s[8:9], 0, v[2:3]
	global_load_dword v1, v[2:3], off
	s_nop 0
	global_load_dword v2, v[2:3], off offset:32
	v_readlane_b32 s8, v241, 19
	v_readlane_b32 s9, v241, 20
	s_waitcnt vmcnt(1)
	v_mul_f32_e32 v3, 0xbfb8aa3b, v1
	v_fma_f32 v4, v1, s42, -v3
	v_rndne_f32_e32 v5, v3
	v_fmac_f32_e32 v4, 0xb2a5705f, v1
	v_sub_f32_e32 v3, v3, v5
	v_add_f32_e32 v3, v3, v4
	v_exp_f32_e32 v3, v3
	v_cvt_i32_f32_e32 v4, v5
	v_cmp_nlt_f32_e32 vcc, s43, v1
	v_ldexp_f32 v3, v3, v4
	s_nop 0
	v_cndmask_b32_e32 v3, 0, v3, vcc
	v_cmp_ngt_f32_e32 vcc, s44, v1
	s_nop 1
	v_cndmask_b32_e32 v1, v150, v3, vcc
	global_load_dword v3, v85, s[8:9]
	s_mov_b32 s8, 0xb2a5705f
	v_add_f32_e32 v1, 1.0, v1
	s_waitcnt vmcnt(0)
	v_add_f32_e32 v2, v2, v3
	v_mul_f32_e64 v3, |v2|, s42
	v_fma_f32 v5, |v2|, s42, -v3
	v_rndne_f32_e32 v6, v3
	v_fma_f32 v5, |v2|, s8, v5
	v_sub_f32_e32 v3, v3, v6
	v_add_f32_e32 v3, v3, v5
	v_exp_f32_e32 v3, v3
	v_cvt_i32_f32_e32 v5, v6
	v_cmp_ngt_f32_e64 vcc, |v2|, s43
	v_max_f32_e32 v4, 0, v2
	s_mov_b32 s8, 0x3f2aaaab
	v_ldexp_f32 v3, v3, v5
	v_cndmask_b32_e32 v3, 0, v3, vcc
	v_cmp_nlt_f32_e64 vcc, |v2|, s44
	s_nop 1
	v_cndmask_b32_e32 v5, v150, v3, vcc
	v_add_f32_e32 v6, 1.0, v5
	v_add_f32_e32 v2, -1.0, v6
	v_sub_f32_e32 v3, v2, v6
	v_add_f32_e32 v3, 1.0, v3
	v_sub_f32_e32 v2, v5, v2
	v_add_f32_e32 v7, v2, v3
	v_frexp_mant_f32_e32 v2, v6
	v_cmp_gt_f32_e32 vcc, s8, v2
	v_cvt_f64_f32_e32 v[2:3], v6
	v_frexp_exp_i32_f64_e32 v2, v[2:3]
	v_subbrev_co_u32_e32 v2, vcc, 0, v2, vcc
	v_sub_u32_e32 v3, 0, v2
	v_ldexp_f32 v6, v6, v3
	v_ldexp_f32 v3, v7, v3
	v_add_f32_e32 v7, -1.0, v6
	v_add_f32_e32 v8, 1.0, v7
	v_sub_f32_e32 v8, v6, v8
	v_add_f32_e32 v8, v3, v8
	v_add_f32_e32 v9, v7, v8
	v_sub_f32_e32 v7, v7, v9
	v_add_f32_e32 v7, v8, v7
	v_add_f32_e32 v8, 1.0, v6
	v_add_f32_e32 v10, -1.0, v8
	v_sub_f32_e32 v6, v6, v10
	v_add_f32_e32 v3, v3, v6
	v_add_f32_e32 v6, v8, v3
	v_sub_f32_e32 v8, v8, v6
	v_add_f32_e32 v3, v3, v8
	v_rcp_f32_e32 v8, v6
	v_cvt_f32_i32_e32 v2, v2
	s_mov_b32 s8, 0x3f317218
	v_mul_f32_e32 v10, v9, v8
	v_mul_f32_e32 v11, v6, v10
	v_fma_f32 v12, v10, v6, -v11
	v_fmac_f32_e32 v12, v10, v3
	v_add_f32_e32 v13, v11, v12
	v_sub_f32_e32 v14, v9, v13
	v_sub_f32_e32 v9, v9, v14
	v_sub_f32_e32 v11, v13, v11
	v_sub_f32_e32 v9, v9, v13
	v_add_f32_e32 v7, v7, v9
	v_sub_f32_e32 v9, v11, v12
	v_add_f32_e32 v7, v9, v7
	v_add_f32_e32 v9, v14, v7
	v_mul_f32_e32 v11, v8, v9
	v_mul_f32_e32 v12, v6, v11
	v_fma_f32 v6, v11, v6, -v12
	v_fmac_f32_e32 v6, v11, v3
	v_sub_f32_e32 v3, v14, v9
	v_add_f32_e32 v3, v7, v3
	v_add_f32_e32 v7, v12, v6
	v_sub_f32_e32 v13, v9, v7
	v_sub_f32_e32 v9, v9, v13
	v_sub_f32_e32 v12, v7, v12
	v_sub_f32_e32 v7, v9, v7
	v_add_f32_e32 v3, v3, v7
	v_sub_f32_e32 v6, v12, v6
	v_add_f32_e32 v3, v6, v3
	v_add_f32_e32 v6, v10, v11
	v_add_f32_e32 v3, v13, v3
	v_sub_f32_e32 v7, v6, v10
	v_mul_f32_e32 v3, v8, v3
	v_sub_f32_e32 v7, v11, v7
	v_add_f32_e32 v3, v7, v3
	v_mul_f32_e32 v10, 0x3f317218, v2
	v_add_f32_e32 v7, v6, v3
	v_fma_f32 v11, v2, s8, -v10
	v_mul_f32_e32 v8, v7, v7
	v_fmac_f32_e32 v11, 0xb102e308, v2
	v_sub_f32_e32 v2, v7, v6
	v_fmamk_f32 v9, v8, 0x3e9b6dac, v147
	v_sub_f32_e32 v2, v3, v2
	v_add_f32_e32 v3, v10, v11
	v_fmaak_f32 v9, v8, v9, 0x3f2aaada
	v_sub_f32_e32 v6, v3, v10
	v_ldexp_f32 v10, v7, 1
	v_mul_f32_e32 v7, v7, v8
	v_mul_f32_e32 v7, v7, v9
	v_add_f32_e32 v8, v10, v7
	v_sub_f32_e32 v9, v8, v10
	v_ldexp_f32 v2, v2, 1
	v_sub_f32_e32 v7, v7, v9
	v_add_f32_e32 v2, v2, v7
	v_add_f32_e32 v7, v8, v2
	v_sub_f32_e32 v8, v7, v8
	v_sub_f32_e32 v2, v2, v8
	v_add_f32_e32 v8, v3, v7
	v_sub_f32_e32 v9, v8, v3
	v_sub_f32_e32 v10, v8, v9
	v_sub_f32_e32 v6, v11, v6
	v_sub_f32_e32 v3, v3, v10
	v_sub_f32_e32 v7, v7, v9
	v_add_f32_e32 v3, v7, v3
	v_add_f32_e32 v7, v6, v2
	v_sub_f32_e32 v9, v7, v6
	v_sub_f32_e32 v10, v7, v9
	v_sub_f32_e32 v6, v6, v10
	v_sub_f32_e32 v2, v2, v9
	v_add_f32_e32 v3, v7, v3
	v_add_f32_e32 v2, v2, v6
	v_add_f32_e32 v6, v8, v3
	v_sub_f32_e32 v7, v6, v8
	v_sub_f32_e32 v3, v3, v7
	v_add_f32_e32 v2, v2, v3
	s_mov_b32 s8, 0x7f800000
	v_add_f32_e32 v2, v6, v2
	v_cmp_neq_f32_e32 vcc, s8, v5
	s_mov_b32 s8, 0x33800000
	s_nop 0
	v_cndmask_b32_e32 v2, v150, v2, vcc
	v_cmp_lt_f32_e64 vcc, |v5|, s8
	v_readlane_b32 s8, v241, 21
	v_readlane_b32 s9, v241, 22
	v_cndmask_b32_e32 v2, v2, v5, vcc
	v_add_f32_e32 v2, v4, v2
	s_nop 2
	global_load_dword v3, v85, s[8:9]
	s_mov_b32 s8, 0x3fb8aa3b
	s_waitcnt vmcnt(0)
	v_mul_f32_e32 v4, 0x3fb8aa3b, v3
	v_fma_f32 v5, v3, s8, -v4
	v_rndne_f32_e32 v6, v4
	v_fmac_f32_e32 v5, 0x32a5705f, v3
	v_sub_f32_e32 v4, v4, v6
	v_add_f32_e32 v4, v4, v5
	v_exp_f32_e32 v4, v4
	v_cvt_i32_f32_e32 v5, v6
	s_mov_b32 s8, 0xc2ce8ed0
	v_cmp_ngt_f32_e32 vcc, s8, v3
	s_mov_b32 s8, 0x42b17218
	v_ldexp_f32 v4, v4, v5
	v_cndmask_b32_e32 v4, 0, v4, vcc
	v_cmp_nlt_f32_e32 vcc, s8, v3
	v_add_u32_e32 v5, -1, v159
	s_nop 0
	v_cndmask_b32_e32 v3, v150, v4, vcc
	v_cmp_lt_i32_e32 vcc, v5, v97
	v_mul_f32_e64 v4, v2, -v3
	s_nop 0
	v_cndmask_b32_e32 v5, v5, v159, vcc
	v_lshlrev_b32_e32 v5, 2, v5
	ds_bpermute_b32 v5, v5, v4
	v_cmp_gt_i32_e32 vcc, 1, v0
	s_waitcnt lgkmcnt(0)
	v_fma_f32 v2, v2, -v3, v5
	v_add_u32_e32 v3, -2, v159
	v_cndmask_b32_e32 v2, v2, v4, vcc
	v_cmp_lt_i32_e32 vcc, v3, v97
	v_div_scale_f32 v4, s[8:9], v1, v1, 1.0
	s_nop 0
	v_cndmask_b32_e32 v3, v3, v159, vcc
	v_lshlrev_b32_e32 v3, 2, v3
	ds_bpermute_b32 v3, v3, v2
	v_cmp_gt_i32_e32 vcc, 2, v0
	v_rcp_f32_e32 v5, v4
	s_and_b32 s8, s85, 0x80
	s_lshl_b32 s8, s8, 2
	s_waitcnt lgkmcnt(0)
	v_add_f32_e32 v3, v2, v3
	v_cndmask_b32_e32 v2, v3, v2, vcc
	v_add_u32_e32 v3, -4, v159
	v_cmp_lt_i32_e32 vcc, v3, v97
	v_fma_f32 v6, -v4, v5, 1.0
	v_fmac_f32_e32 v5, v6, v5
	v_cndmask_b32_e32 v3, v3, v159, vcc
	v_lshlrev_b32_e32 v3, 2, v3
	ds_bpermute_b32 v3, v3, v2
	v_cmp_gt_i32_e32 vcc, 4, v0
	s_add_i32 s8, s18, s8
	s_waitcnt lgkmcnt(0)
	v_add_f32_e32 v3, v2, v3
	v_cndmask_b32_e32 v2, v3, v2, vcc
	v_add_u32_e32 v3, -8, v159
	v_cmp_lt_i32_e32 vcc, v3, v97
	s_nop 1
	v_cndmask_b32_e32 v3, v3, v159, vcc
	v_lshlrev_b32_e32 v3, 2, v3
	ds_bpermute_b32 v3, v3, v2
	v_cmp_gt_i32_e32 vcc, 8, v0
	s_waitcnt lgkmcnt(0)
	v_add_f32_e32 v3, v2, v3
	v_cndmask_b32_e32 v2, v3, v2, vcc
	v_add_u32_e32 v3, -16, v159
	v_cmp_lt_i32_e32 vcc, v3, v97
	s_nop 1
	v_cndmask_b32_e32 v3, v3, v159, vcc
	v_lshlrev_b32_e32 v3, 2, v3
	ds_bpermute_b32 v3, v3, v2
	v_cmp_gt_i32_e32 vcc, 16, v0
	s_waitcnt lgkmcnt(0)
	v_add_f32_e32 v3, v2, v3
	v_cndmask_b32_e32 v3, v3, v2, vcc
	v_subrev_u32_e32 v2, 32, v159
	v_cmp_lt_i32_e32 vcc, v2, v97
	s_nop 1
	v_cndmask_b32_e32 v2, v2, v159, vcc
	v_lshlrev_b32_e32 v2, 2, v2
	ds_bpermute_b32 v2, v2, v3
	v_cmp_gt_i32_e32 vcc, 32, v0
	s_waitcnt lgkmcnt(0)
	v_add_f32_e32 v2, v3, v2
	v_cndmask_b32_e32 v3, v2, v3, vcc
	v_div_scale_f32 v6, vcc, 1.0, v1, 1.0
	v_mul_f32_e32 v7, v6, v5
	v_fma_f32 v8, -v4, v7, v6
	v_fmac_f32_e32 v7, v8, v5
	v_fma_f32 v4, -v4, v7, v6
	v_div_fmas_f32 v4, v4, v5, v7
	v_div_fixup_f32 v1, v4, v1, 1.0
	v_lshl_add_u32 v4, v0, 2, s8
	v_cmp_eq_u32_e32 vcc, 63, v0
	ds_write2st64_b32 v4, v3, v1 offset1:1
	s_and_saveexec_b64 s[8:9], vcc
	s_cbranch_execz .LBB0_225
	v_mul_f32_e32 v0, 0x3fb8aa3b, v2
	v_rndne_f32_e32 v1, v0
	s_mov_b32 s42, 0x3fb8aa3b
	v_sub_f32_e32 v3, v0, v1
	v_fma_f32 v0, v2, s42, -v0
	v_fmac_f32_e32 v0, 0x32a5705f, v2
	v_add_f32_e32 v0, v3, v0
	v_exp_f32_e32 v0, v0
	v_cvt_i32_f32_e32 v1, v1
	s_mov_b32 s43, 0xc2ce8ed0
	s_add_i32 s42, s72, 8
	v_cmp_ngt_f32_e32 vcc, s43, v2
	v_ldexp_f32 v0, v0, v1
	s_mov_b32 s43, 0x42b17218
	v_cndmask_b32_e32 v0, 0, v0, vcc
	v_cmp_nlt_f32_e32 vcc, s43, v2
	s_ashr_i32 s43, s42, 31
	s_lshl_b64 s[42:43], s[42:43], 2
	v_readlane_b32 s44, v241, 7
	v_readlane_b32 s45, v241, 8
	s_add_u32 s42, s44, s42
	v_cndmask_b32_e32 v0, v150, v0, vcc
	s_addc_u32 s43, s45, s43
	global_store_dword v85, v0, s[42:43]
	s_branch .LBB0_225

.LBB0_308:
	s_waitcnt vmcnt(0)
	v_readfirstlane_b32 s4, v194
	s_cmp_gt_u32 s4, 63
	v_readlane_b32 s77, v242, 9
	v_readlane_b32 s78, v241, 13
	v_readlane_b32 s40, v241, 12
	v_readlane_b32 s41, v241, 4
	s_barrier
	s_cbranch_scc1 .LBB0_362
	v_mbcnt_lo_u32_b32 v0, -1, 0
	v_mbcnt_hi_u32_b32 v0, -1, v0
	s_nop 0
	v_cmp_eq_u32_e32 vcc, 0, v0
	s_and_saveexec_b64 s[6:7], vcc
	s_cbranch_execz .LBB0_361
	v_mov_b32_e32 v0, 0x23ff0
	s_waitcnt vmcnt(0) lgkmcnt(0)
	ds_read_b128 v[0:3], v0
	s_waitcnt lgkmcnt(0)
	v_readfirstlane_b32 s8, v2
	s_nop 0
	s_cmp_eq_u32 s8, 0
	s_cbranch_scc1 .Lfb_slow_1
	v_add_u32_e32 v3, 1, v3
	v_mov_b32_e32 v4, 0x23ffc
	ds_write_b32 v4, v3
	v_mul_lo_u32 v5, v3, v0
	s_getreg_b32 s8, hwreg(HW_REG_XCC_ID, 0, 4)
	s_and_b32 s8, s8, 7
	s_lshl_b32 s8, s8, 8
	s_add_u32 s8, s8, 0x3680
	s_add_u32 s4, s92, 0x510000
	s_addc_u32 s5, s93, 0
	v_mov_b32_e32 v6, s8
	v_mov_b32_e32 v7, 1
	global_atomic_add v6, v7, s[4:5]
	s_mov_b32 s9, 0
.Lfb_spin_1:
	global_load_dword v8, v6, s[4:5] sc1
	s_waitcnt vmcnt(0)
	v_cmp_ge_u32_e32 vcc, v8, v5
	s_cbranch_vccnz .Lfb_done_1
	s_sleep 1
	s_add_u32 s9, s9, 1
	s_cmp_lt_u32 s9, 0x40000
	s_cbranch_scc1 .Lfb_spin_1

.Lfb_slow_1:
	s_add_i32 s4, 0, 0x23ff0
	v_mov_b32_e32 v0, s4
	s_waitcnt vmcnt(0) expcnt(0) lgkmcnt(0)
	ds_read_b32 v2, v0
	s_add_i32 s4, 0, 0x23ff4
	v_mov_b32_e32 v0, s4
	ds_read_b32 v0, v0
	s_waitcnt lgkmcnt(1)
	v_cmp_ne_u32_e32 vcc, 0, v2
	s_cbranch_vccnz .LBB0_325
	s_mov_b32 s4, 1
	v_mov_b32_e32 v16, 0
	s_branch .LBB0_313

.LBB0_341:
	s_andn2_saveexec_b64 s[4:5], s[8:9]
	s_cbranch_execz .LBB0_361
	v_mov_b32_e32 v1, 0x23ff8
	ds_read_b32 v1, v1
	s_waitcnt lgkmcnt(0)
	v_readfirstlane_b32 s4, v1
	s_nop 0
	s_cmp_lg_u32 s4, 0
	s_cbranch_scc1 .Lxloc_1
	s_mov_b64 s[8:9], exec
	buffer_wbl2 sc1
	s_waitcnt lgkmcnt(0)
	s_waitcnt vmcnt(0)
	v_mbcnt_lo_u32_b32 v1, s8, 0
	v_mbcnt_hi_u32_b32 v1, s9, v1
	v_cmp_eq_u32_e32 vcc, 0, v1
	s_and_saveexec_b64 s[12:13], vcc
	s_cbranch_execz .LBB0_344
	s_bcnt1_i32_b64 s4, s[8:9]
	v_mov_b32_e32 v3, s4
	v_readlane_b32 s4, v240, 24
	v_mov_b32_e32 v2, 0
	v_readlane_b32 s5, v240, 25
	s_nop 4
	global_atomic_add v2, v2, v3, s[4:5] sc0

.Lxloc_1:
	s_mov_b64 s[8:9], exec
	v_mbcnt_lo_u32_b32 v0, s8, 0
	v_mbcnt_hi_u32_b32 v0, s9, v0
	v_cmp_eq_u32_e32 vcc, 0, v0
	s_waitcnt vmcnt(0)
	buffer_inv sc1
	s_and_saveexec_b64 s[12:13], vcc
	s_cbranch_execz .LBB0_360
	s_bcnt1_i32_b64 s4, s[8:9]
	v_mov_b32_e32 v1, s4
	v_readlane_b32 s4, v240, 22
	v_mov_b32_e32 v0, 0
	v_readlane_b32 s5, v240, 23
	s_nop 4
	global_atomic_add v0, v1, s[4:5]

.LBB0_362:
	v_readlane_b32 s4, v242, 8
	s_waitcnt lgkmcnt(0)
	s_barrier
	v_mbcnt_lo_u32_b32 v0, -1, 0
	v_mbcnt_hi_u32_b32 v0, -1, v0
	v_mov_b32_e32 v30, 0
	s_mov_b32 s4, s40
	s_mov_b32 s5, s77
	v_and_b32_e32 v1, 15, v0
	v_lshrrev_b32_e32 v2, 4, v0
	s_lshr_b32 s38, s5, 1
	s_and_b32 s39, s5, 1
	s_lshr_b32 s7, s4, 2
	s_lshl_b32 s7, s7, 5
	s_and_b32 s8, s4, 3
	s_lshl_b32 s9, s7, 14
	s_add_u32 s10, s92, 0x9000000
	s_addc_u32 s11, s93, 0
	s_add_u32 s10, s10, s9
	s_addc_u32 s11, s11, 0
	s_add_u32 s12, s92, 0xb000000
	s_addc_u32 s13, s93, 0
	s_add_u32 s12, s12, s9
	s_addc_u32 s13, s13, 0
	s_add_u32 s14, s92, 0xd000000
	s_addc_u32 s15, s93, 0
	s_add_u32 s14, s14, s9
	s_addc_u32 s15, s15, 0
	s_lshl_b32 s26, s7, 13
	s_add_u32 s18, s92, 0xf000000
	s_addc_u32 s19, s93, 0
	s_add_u32 s18, s18, s26
	s_addc_u32 s19, s19, 0
	s_add_u32 s24, s90, 0x2000000
	s_addc_u32 s25, s91, 0
	s_add_u32 s24, s24, s9
	s_addc_u32 s25, s25, 0
	s_lshl_b32 s26, s8, 6
	s_add_u32 s24, s24, s26
	s_addc_u32 s25, s25, 0
	s_add_u32 s42, s92, 0x500000
	s_addc_u32 s43, s93, 0
	v_and_b32_e32 v26, 31, v0
	v_add_u32_e32 v26, s7, v26
	v_lshlrev_b32_e32 v26, 2, v26
	global_load_dword v24, v26, s[42:43]
	v_mov_b32_e32 v30, 0
	s_lshl_b32 s30, s5, 11
	s_lshl_b32 s31, s5, 10
	s_and_b32 s32, s5, 3
	s_lshl_b32 s32, s32, 10
	s_lshl_b32 s7, s5, 3
	v_add_u32_e32 v26, s7, v2
	v_and_b32_e32 v27, 15, v26
	v_xor_b32_e32 v27, v27, v1
	v_lshlrev_b32_e32 v27, 4, v27
	v_lshl_add_u32 v3, v26, 8, v27
	s_lshl_b32 s7, s5, 3
	s_add_u32 s7, s7, 4
	v_add_u32_e32 v26, s7, v2
	v_and_b32_e32 v27, 15, v26
	v_xor_b32_e32 v27, v27, v1
	v_lshlrev_b32_e32 v27, 4, v27
	v_lshl_add_u32 v4, v26, 8, v27
	v_lshrrev_b32_e32 v28, 3, v0
	v_and_b32_e32 v29, 7, v0
	s_lshl_b32 s7, s5, 4
	v_add_u32_e32 v26, s7, v28
	v_bfe_u32 v27, v26, 1, 3
	v_xor_b32_e32 v27, v27, v29
	v_lshlrev_b32_e32 v27, 4, v27
	v_lshl_add_u32 v5, v26, 7, v27
	s_lshl_b32 s7, s5, 4
	s_add_u32 s7, s7, 8
	v_add_u32_e32 v26, s7, v28
	v_bfe_u32 v27, v26, 1, 3
	v_xor_b32_e32 v27, v27, v29
	v_lshlrev_b32_e32 v27, 4, v27
	v_lshl_add_u32 v6, v26, 7, v27
	s_lshl_b32 s7, s5, 3
	v_add_u32_e32 v26, s7, v28
	v_bfe_u32 v27, v26, 1, 3
	v_xor_b32_e32 v27, v27, v29
	v_lshlrev_b32_e32 v27, 4, v27
	v_lshl_add_u32 v7, v26, 7, v27
	s_and_b32 s7, s5, 3
	s_lshl_b32 s7, s7, 4
	v_lshrrev_b32_e32 v26, 2, v0
	v_add_u32_e32 v26, s7, v26
	v_and_b32_e32 v27, 3, v0
	v_lshlrev_b32_e32 v27, 4, v27
	v_lshl_add_u32 v8, v26, 8, v27
	s_lshl_b32 s7, s39, 4
	v_add_u32_e32 v26, s7, v1
	s_lshl_b32 s8, s38, 4
	v_add_u32_e32 v27, s8, v1
	v_lshlrev_b32_e32 v28, 4, v2
	s_movk_i32 s9, 0x110
	v_mul_lo_u32 v29, v26, s9
	v_add_u32_e32 v10, v29, v28
	v_add_u32_e32 v10, 0x1c000, v10
	v_lshlrev_b32_e32 v31, 3, v2
	s_lshl_b32 s9, s38, 6
	v_add3_u32 v21, v29, v31, s9
	v_add_u32_e32 v21, 0x1c000, v21
	s_movk_i32 s9, 0x90
	v_mul_lo_u32 v29, v26, s9
	v_add_u32_e32 v19, v29, v28
	v_add_u32_e32 v19, 0x1e200, v19
	s_lshl_b32 s9, s38, 5
	v_add3_u32 v20, v29, v31, s9
	v_add_u32_e32 v20, 0x1e200, v20
	v_add_u32_e32 v29, 0, v2
	v_xor_b32_e32 v29, v29, v1
	v_lshlrev_b32_e32 v29, 4, v29
	v_lshl_add_u32 v11, v27, 8, v29
	v_add_u32_e32 v29, 4, v2
	v_xor_b32_e32 v29, v29, v1
	v_lshlrev_b32_e32 v29, 4, v29
	v_lshl_add_u32 v12, v27, 8, v29
	v_add_u32_e32 v29, 8, v2
	v_xor_b32_e32 v29, v29, v1
	v_lshlrev_b32_e32 v29, 4, v29
	v_lshl_add_u32 v13, v27, 8, v29
	v_add_u32_e32 v29, 12, v2
	v_xor_b32_e32 v29, v29, v1
	v_lshlrev_b32_e32 v29, 4, v29
	v_lshl_add_u32 v14, v27, 8, v29
	v_lshrrev_b32_e32 v31, 1, v1
	s_lshl_b32 s9, s38, 5
	v_add_u32_e32 v26, s9, v1
	v_add_u32_e32 v29, 0, v2
	v_xor_b32_e32 v29, v29, v31
	v_lshlrev_b32_e32 v29, 4, v29
	v_lshl_add_u32 v15, v26, 7, v29
	v_add_u32_e32 v15, 0x10000, v15
	v_lshl_add_u32 v17, v27, 7, v29
	v_add_u32_e32 v17, 0x18000, v17
	v_add_u32_e32 v29, 4, v2
	v_xor_b32_e32 v29, v29, v31
	v_lshlrev_b32_e32 v29, 4, v29
	v_lshl_add_u32 v16, v26, 7, v29
	v_add_u32_e32 v16, 0x10000, v16
	v_lshl_add_u32 v18, v27, 7, v29
	v_add_u32_e32 v18, 0x18000, v18
	s_lshl_b32 s9, s38, 10
	v_lshlrev_b32_e32 v29, 8, v2
	v_add_u32_e32 v29, s9, v29
	s_lshl_b32 s9, s39, 5
	v_lshl_add_u32 v29, v1, 1, v29
	v_add_u32_e32 v29, s9, v29
	v_add_u32_e32 v22, 0x1f400, v29
	v_lshlrev_b32_e32 v29, 3, v2
	v_lshl_add_u32 v29, v27, 8, v29
	v_add_u32_e32 v9, s9, v29
	v_mov_b32_e32 v32, 0
	v_mov_b32_e32 v33, 0
	v_mov_b32_e32 v34, 0
	v_mov_b32_e32 v35, 0
	v_lshl_add_u32 v26, s5, 6, v0
	v_lshlrev_b32_e32 v27, 4, v26
	v_add_u32_e32 v27, 0x1c000, v27
	ds_write_b128 v27, v[32:35]
	v_and_b32_e32 v26, 31, v26
	v_lshlrev_b32_e32 v27, 4, v26
	v_add_u32_e32 v27, 0x1e000, v27
	ds_write_b128 v27, v[32:35]
	v_mov_b32_e32 v92, 0
	v_mov_b32_e32 v93, 0
	v_mov_b32_e32 v94, 0
	v_mov_b32_e32 v95, 0
	v_mov_b32_e32 v96, 0
	v_mov_b32_e32 v97, 0
	v_mov_b32_e32 v98, 0
	v_mov_b32_e32 v99, 0
	s_mov_b32 s6, 0
	global_load_dword v25, v30, s[42:43]
	global_load_dword v25, v30, s[42:43]
	global_load_dword v25, v30, s[42:43]
	s_add_i32 m0, s32, 0x1f400
	s_nop 0
	global_load_lds_dwordx4 v8, s[24:25]
	s_add_i32 m0, s30, 0x0
	s_nop 0
	global_load_lds_dwordx4 v3, s[10:11]
	s_add_i32 m0, s30, 0x400
	s_nop 0
	global_load_lds_dwordx4 v4, s[10:11]
	s_add_i32 m0, s30, 0x8000
	s_nop 0
	global_load_lds_dwordx4 v3, s[12:13]
	s_add_i32 m0, s30, 0x8400
	s_nop 0
	global_load_lds_dwordx4 v4, s[12:13]
	global_load_dword v25, v30, s[42:43]
	s_add_i32 m0, s30, 0x10000
	s_nop 0
	global_load_lds_dwordx4 v5, s[14:15]
	s_add_i32 m0, s30, 0x10400
	s_nop 0
	global_load_lds_dwordx4 v6, s[14:15]
	s_add_i32 m0, s31, 0x18000
	s_nop 0
	global_load_lds_dwordx4 v7, s[18:19]
	s_add_u32 s26, s24, 0x4000
	s_addc_u32 s27, s25, 0
	s_add_i32 m0, s32, 0x20400
	s_nop 0
	global_load_lds_dwordx4 v8, s[26:27]
	s_add_u32 s26, s10, 0x4000
	s_addc_u32 s27, s11, 0
	s_add_i32 m0, s30, 0x4000
	s_nop 0
	global_load_lds_dwordx4 v3, s[26:27]
	s_add_i32 m0, s30, 0x4400
	s_nop 0
	global_load_lds_dwordx4 v4, s[26:27]
	s_add_u32 s26, s12, 0x4000
	s_addc_u32 s27, s13, 0
	s_add_i32 m0, s30, 0xc000
	s_nop 0
	global_load_lds_dwordx4 v3, s[26:27]
	s_add_i32 m0, s30, 0xc400
	s_nop 0
	global_load_lds_dwordx4 v4, s[26:27]
	global_load_dword v25, v30, s[42:43]
	s_waitcnt vmcnt(10) lgkmcnt(0)
	s_barrier
